# stack on sw7: P8 epilogue early issue of row +0xa0/+0xb0 loads with vmcnt(4), silu -log2e/+1.0 as v_pk ops, wr==1 stagger barrier moved behind unit bookkeeping
# baseline (speedup 1.0000x reference)
; #define PG8_STAGE(bufoff, gbase, voff) do { _Pragma("unroll") for (int _i = 0; _i < 2; ++_i) \
;         __builtin_amdgcn_global_load_lds((const unsigned*)((const char*)(gbase) + (voff)[_i]), (LAS unsigned*)(lds + (bufoff) + ldsw + _i * 8192), 16, 0, 0); } while (0)
; #define PG8_LDA(dst, b, h) do { _Pragma("unroll") for (int m = 0; m < 4; ++m) _Pragma("unroll") for (int k = 0; k < 2; ++k) dst[m][k] = *(const LAS bf16x8*)(lds + PG8_SA(b, h) + aoff + m * 2048 + k * 1024); } while (0)
; #define PG8_LDB(dst, b, h) do { _Pragma("unroll") for (int n = 0; n < 2; ++n) _Pragma("unroll") for (int k = 0; k < 2; ++k) dst[n][k] = *(const LAS bf16x8*)(lds + PG8_SB(b, h) + boff + n * 2048 + k * 1024); } while (0)
; #define PG8_MMA(ai, bj, At, Bt) do { __builtin_amdgcn_s_setprio(1); _Pragma("unroll") for (int m = 0; m < 4; ++m) _Pragma("unroll") for (int n = 0; n < 2; ++n) _Pragma("unroll") for (int k = 0; k < 2; ++k) \
;         acc[ai][bj][m][n] = __builtin_amdgcn_mfma_f32_16x16x32_bf16(Bt[n][k], At[m][k], acc[ai][bj][m][n], 0, 0, 0); __builtin_amdgcn_s_setprio(0); } while (0)
; #define PG8_WAIT_V(n) asm volatile("s_waitcnt vmcnt(" #n ")" ::: "memory")
; #define PG8_WAIT_L(n) asm volatile("s_waitcnt lgkmcnt(" #n ")" ::: "memory")
; #define PG8_BAR __builtin_amdgcn_s_barrier()
; #define PG8_SCHED __builtin_amdgcn_sched_barrier(0)
; template <class Epi>
; __device__ __forceinline__ void gemm_phase(LAS unsigned char* lds, const bf16_t* A0, const bf16_t* B0, const bf16_t* A1, const bf16_t* B1, const int K, const Order& S, const Epi& E) {
;     ...
;             PG8_LDB(Bf0, 0, 0); PG8_LDB(Bf1, 0, 1); PG8_SCHED; PG8_LDA(At, 0, 0); PG8_STAGE(PG8_SA(1, 1), a1 + hstep, voffA);
;             PG8_WAIT_V(8); PG8_WAIT_L(0); PG8_BAR; PG8_MMA(0, 0, At, Bf0); PG8_MMA(0, 1, At, Bf1); PG8_BAR; PG8_SCHED;
;     ...
; #pragma unroll
;         for (int a = 0; a < 2; ++a)
; #pragma unroll
;             for (int b = 0; b < 2; ++b)
; #pragma unroll
;                 for (int m = 0; m < 4; ++m)
; #pragma unroll
;                     for (int n = 0; n < 2; ++n) acc[a][b][m][n] = (f32x4){0.f, 0.f, 0.f, 0.f};
;         cur = nxt; cA = nA; cB = nB; ++ui;
;         if (wr == 1) PG8_BAR;
.LBB0_1153:
	s_ashr_i32 s63, s62, 31
	s_lshl_b64 s[12:13], s[62:63], 20
	s_add_u32 s64, s88, s12
	s_addc_u32 s65, s89, s13
	s_ashr_i32 s61, s60, 31
	s_lshl_b64 s[12:13], s[60:61], 20
	v_readlane_b32 s66, v243, 21
	v_readlane_b32 s67, v243, 22
	s_add_u32 s66, s66, s12
	s_addc_u32 s67, s67, s13
	s_cmpk_lt_i32 s1, 0x1760
	s_cselect_b64 s[68:69], -1, 0
	s_and_b64 s[12:13], s[68:69], exec
	s_cselect_b32 s1, s65, s9
	s_cselect_b32 s61, s64, s8
	s_cselect_b32 s63, s67, s11
	s_cselect_b32 s71, s66, s10
	s_add_u32 s8, s8, 0x80080
	s_addc_u32 s9, s9, 0
	s_add_u32 s72, s10, 0x100
	v_mov_b32_e32 v0, 0
	s_addc_u32 s73, s11, 0
	s_mov_b32 s74, -2
	v_mov_b32_e32 v1, v0
	v_mov_b64_e32 v[2:3], 0
	v_mov_b64_e32 v[4:5], 0
	v_mov_b64_e32 v[6:7], 0
	v_mov_b64_e32 v[8:9], 0
	v_mov_b64_e32 v[10:11], 0
	v_mov_b64_e32 v[12:13], 0
	v_mov_b64_e32 v[14:15], 0
	v_mov_b64_e32 v[16:17], 0
	v_mov_b64_e32 v[18:19], 0
	v_mov_b64_e32 v[20:21], 0
	v_mov_b64_e32 v[22:23], 0
	v_mov_b64_e32 v[32:33], 0
	v_mov_b64_e32 v[34:35], 0
	v_mov_b64_e32 v[36:37], 0
	v_mov_b64_e32 v[38:39], 0
	v_mov_b64_e32 v[56:57], 0
	v_mov_b64_e32 v[58:59], 0
	v_mov_b64_e32 v[60:61], 0
	v_mov_b64_e32 v[62:63], 0
	v_mov_b64_e32 v[24:25], 0
	v_mov_b64_e32 v[26:27], 0
	v_mov_b64_e32 v[28:29], 0
	v_mov_b64_e32 v[30:31], 0
	v_mov_b64_e32 v[40:41], 0
	v_mov_b64_e32 v[42:43], 0
	v_mov_b64_e32 v[44:45], 0
	v_mov_b64_e32 v[46:47], 0
	v_mov_b64_e32 v[48:49], 0
	v_mov_b64_e32 v[50:51], 0
	v_mov_b64_e32 v[52:53], 0
	v_mov_b64_e32 v[54:55], 0
	s_waitcnt vmcnt(0)
	v_mov_b64_e32 v[112:113], 0
	v_mov_b64_e32 v[114:115], 0
	v_mov_b64_e32 v[116:117], 0
	v_mov_b64_e32 v[118:119], 0
	v_mov_b64_e32 v[120:121], 0
	v_mov_b64_e32 v[122:123], 0
	v_mov_b64_e32 v[124:125], 0
	v_mov_b64_e32 v[126:127], 0
	v_mov_b64_e32 v[136:137], 0
	v_mov_b64_e32 v[138:139], 0
	v_mov_b64_e32 v[140:141], 0
	v_mov_b64_e32 v[142:143], 0
	v_mov_b64_e32 v[88:89], 0
	v_mov_b64_e32 v[90:91], 0
	v_mov_b64_e32 v[92:93], 0
	v_mov_b64_e32 v[94:95], 0
	v_mov_b64_e32 v[64:65], 0
	v_mov_b64_e32 v[66:67], 0
	v_mov_b64_e32 v[68:69], 0
	v_mov_b64_e32 v[70:71], 0
	v_mov_b64_e32 v[128:129], 0
	v_mov_b64_e32 v[130:131], 0
	v_mov_b64_e32 v[132:133], 0
	v_mov_b64_e32 v[134:135], 0
	v_mov_b64_e32 v[144:145], 0
	v_mov_b64_e32 v[146:147], 0
	v_mov_b64_e32 v[148:149], 0
	v_mov_b64_e32 v[150:151], 0
	v_mov_b64_e32 v[96:97], 0
	v_mov_b64_e32 v[98:99], 0
	v_mov_b64_e32 v[100:101], 0
	v_mov_b64_e32 v[102:103], 0
	s_cmp_lt_u32 s78, 2
	s_cbranch_scc1 .Lstg8_skip
	s_and_b64 vcc, exec, s[36:37]
	s_cbranch_vccz .Lstg8_skip
	s_barrier
.Lstg8_skip:
.LBB0_1154:
	ds_read_b128 v[72:75], v232
	ds_read_b128 v[76:79], v232 offset:1024
	ds_read_b128 v[80:83], v232 offset:2048
	ds_read_b128 v[84:87], v232 offset:3072
	ds_read_b128 v[104:107], v233
	ds_read_b128 v[108:111], v233 offset:1024
	ds_read_b128 v[152:155], v233 offset:2048
	ds_read_b128 v[156:159], v233 offset:3072
	s_add_u32 s10, s8, 0xfff80080
	s_addc_u32 s11, s9, -1
	s_cmp_eq_u32 s74, 28
	s_cselect_b32 s13, s1, s11
	s_cselect_b32 s12, s61, s10
	s_cselect_b32 s11, s63, s73
	s_cselect_b32 s10, s71, s72
	v_lshl_add_u64 v[218:219], s[8:9], 0, v[196:197]
	s_add_i32 m0, s35, 0xc000
	ds_read_b128 v[160:163], v234
	ds_read_b128 v[164:167], v234 offset:1024
	ds_read_b128 v[168:171], v234 offset:2048
	ds_read_b128 v[172:175], v234 offset:3072
	ds_read_b128 v[202:205], v234 offset:4096
	ds_read_b128 v[206:209], v234 offset:5120
	ds_read_b128 v[210:213], v234 offset:6144
	ds_read_b128 v[214:217], v234 offset:7168
	global_load_lds_dwordx4 v[218:219], off
	v_lshl_add_u64 v[218:219], s[8:9], 0, v[198:199]
	s_add_i32 m0, s35, 0xe000
	s_nop 0
	global_load_lds_dwordx4 v[218:219], off
	s_waitcnt vmcnt(8)
	s_waitcnt lgkmcnt(0)
	s_barrier
	s_setprio 1
	s_waitcnt lgkmcnt(0)
	v_mfma_f32_16x16x32_bf16 v[100:103], v[72:75], v[160:163], v[100:103]
	v_mfma_f32_16x16x32_bf16 v[96:99], v[80:83], v[160:163], v[96:99]
	v_mfma_f32_16x16x32_bf16 v[148:151], v[72:75], v[168:171], v[148:151]
	v_mfma_f32_16x16x32_bf16 v[144:147], v[80:83], v[168:171], v[144:147]
	v_mfma_f32_16x16x32_bf16 v[132:135], v[72:75], v[202:205], v[132:135]
	v_mfma_f32_16x16x32_bf16 v[128:131], v[80:83], v[202:205], v[128:131]
	v_mfma_f32_16x16x32_bf16 v[68:71], v[72:75], v[210:213], v[68:71]
	v_mfma_f32_16x16x32_bf16 v[64:67], v[80:83], v[210:213], v[64:67]
	v_mfma_f32_16x16x32_bf16 v[100:103], v[76:79], v[164:167], v[100:103]
	v_mfma_f32_16x16x32_bf16 v[96:99], v[84:87], v[164:167], v[96:99]
	v_mfma_f32_16x16x32_bf16 v[148:151], v[76:79], v[172:175], v[148:151]
	v_mfma_f32_16x16x32_bf16 v[144:147], v[84:87], v[172:175], v[144:147]
	v_mfma_f32_16x16x32_bf16 v[132:135], v[76:79], v[206:209], v[132:135]
	v_mfma_f32_16x16x32_bf16 v[128:131], v[84:87], v[206:209], v[128:131]
	v_mfma_f32_16x16x32_bf16 v[68:71], v[76:79], v[214:217], v[68:71]
	v_mfma_f32_16x16x32_bf16 v[64:67], v[84:87], v[214:217], v[64:67]
	s_setprio 0
	s_setprio 1
	v_mfma_f32_16x16x32_bf16 v[92:95], v[104:107], v[160:163], v[92:95]
	v_mfma_f32_16x16x32_bf16 v[88:91], v[152:155], v[160:163], v[88:91]
	v_mfma_f32_16x16x32_bf16 v[140:143], v[104:107], v[168:171], v[140:143]
	v_mfma_f32_16x16x32_bf16 v[136:139], v[152:155], v[168:171], v[136:139]
	v_mfma_f32_16x16x32_bf16 v[124:127], v[104:107], v[202:205], v[124:127]
	v_mfma_f32_16x16x32_bf16 v[120:123], v[152:155], v[202:205], v[120:123]
	v_mfma_f32_16x16x32_bf16 v[116:119], v[104:107], v[210:213], v[116:119]
	v_mfma_f32_16x16x32_bf16 v[112:115], v[152:155], v[210:213], v[112:115]
	v_mfma_f32_16x16x32_bf16 v[92:95], v[108:111], v[164:167], v[92:95]
	v_mfma_f32_16x16x32_bf16 v[88:91], v[156:159], v[164:167], v[88:91]
	v_mfma_f32_16x16x32_bf16 v[140:143], v[108:111], v[172:175], v[140:143]
	v_mfma_f32_16x16x32_bf16 v[136:139], v[156:159], v[172:175], v[136:139]
	v_mfma_f32_16x16x32_bf16 v[124:127], v[108:111], v[206:209], v[124:127]
	v_mfma_f32_16x16x32_bf16 v[120:123], v[156:159], v[206:209], v[120:123]
	v_mfma_f32_16x16x32_bf16 v[116:119], v[108:111], v[214:217], v[116:119]
	v_mfma_f32_16x16x32_bf16 v[112:115], v[156:159], v[214:217], v[112:115]
	s_setprio 0
	s_barrier
; #define PG8_STAGE(bufoff, gbase, voff) do { _Pragma("unroll") for (int _i = 0; _i < 2; ++_i) \
;         __builtin_amdgcn_global_load_lds((const unsigned*)((const char*)(gbase) + (voff)[_i]), (LAS unsigned*)(lds + (bufoff) + ldsw + _i * 8192), 16, 0, 0); } while (0)
; #define PG8_LDA(dst, b, h) do { _Pragma("unroll") for (int m = 0; m < 4; ++m) _Pragma("unroll") for (int k = 0; k < 2; ++k) dst[m][k] = *(const LAS bf16x8*)(lds + PG8_SA(b, h) + aoff + m * 2048 + k * 1024); } while (0)
; #define PG8_LDB(dst, b, h) do { _Pragma("unroll") for (int n = 0; n < 2; ++n) _Pragma("unroll") for (int k = 0; k < 2; ++k) dst[n][k] = *(const LAS bf16x8*)(lds + PG8_SB(b, h) + boff + n * 2048 + k * 1024); } while (0)
; #define PG8_MMA(ai, bj, At, Bt) do { __builtin_amdgcn_s_setprio(1); _Pragma("unroll") for (int m = 0; m < 4; ++m) _Pragma("unroll") for (int n = 0; n < 2; ++n) _Pragma("unroll") for (int k = 0; k < 2; ++k) \
;         acc[ai][bj][m][n] = __builtin_amdgcn_mfma_f32_16x16x32_bf16(Bt[n][k], At[m][k], acc[ai][bj][m][n], 0, 0, 0); __builtin_amdgcn_s_setprio(0); } while (0)
; #define PG8_WAIT_V(n) asm volatile("s_waitcnt vmcnt(" #n ")" ::: "memory")
; #define PG8_WAIT_L(n) asm volatile("s_waitcnt lgkmcnt(" #n ")" ::: "memory")
; #define PG8_BAR __builtin_amdgcn_s_barrier()
; #define PG8_SCHED __builtin_amdgcn_sched_barrier(0)
; template <class Epi>
; __device__ __forceinline__ void gemm_phase(LAS unsigned char* lds, const bf16_t* A0, const bf16_t* B0, const bf16_t* A1, const bf16_t* B1, const int K, const Order& S, const Epi& E) {
;     ...
;             PG8_LDA(At, 0, 1); PG8_STAGE(PG8_SB(0, 0), b2, voffB); PG8_STAGE(PG8_SB(0, 1), b2 + hstep, voffB); PG8_STAGE(PG8_SA(0, 0), a2, voffA);
;             PG8_WAIT_V(8); PG8_WAIT_L(0); PG8_BAR; PG8_MMA(1, 0, At, Bf0); PG8_MMA(1, 1, At, Bf1); PG8_BAR; PG8_SCHED;
;             PG8_LDB(Bf0, 1, 0); PG8_LDB(Bf1, 1, 1); PG8_SCHED; PG8_LDA(At, 1, 0); PG8_STAGE(PG8_SA(0, 1), a2 + hstep, voffA);
;             PG8_WAIT_V(8); PG8_WAIT_L(0); PG8_BAR; PG8_MMA(0, 0, At, Bf0); PG8_MMA(0, 1, At, Bf1); PG8_BAR; PG8_SCHED;
	s_add_i32 s75, s83, s33
	v_lshl_add_u64 v[218:219], s[10:11], 0, v[182:183]
	s_mov_b32 m0, s75
	ds_read_b128 v[160:163], v234 offset:16384
	ds_read_b128 v[164:167], v234 offset:17408
	ds_read_b128 v[168:171], v234 offset:18432
	ds_read_b128 v[172:175], v234 offset:19456
	ds_read_b128 v[202:205], v234 offset:20480
	ds_read_b128 v[206:209], v234 offset:21504
	ds_read_b128 v[210:213], v234 offset:22528
	ds_read_b128 v[214:217], v234 offset:23552
	global_load_lds_dwordx4 v[218:219], off
	s_add_i32 m0, s75, 0x2000
	s_add_u32 s96, s10, 0x80000
	v_lshl_add_u64 v[220:221], s[10:11], 0, v[186:187]
	s_addc_u32 s97, s11, 0
	s_add_i32 s75, s84, s33
	global_load_lds_dwordx4 v[220:221], off
	v_lshl_add_u64 v[222:223], s[96:97], 0, v[182:183]
	s_mov_b32 m0, s75
	v_lshl_add_u64 v[224:225], s[12:13], 0, v[184:185]
	global_load_lds_dwordx4 v[222:223], off
	v_lshl_add_u64 v[222:223], s[96:97], 0, v[186:187]
	s_add_i32 m0, s75, 0x2000
	s_nop 0
	global_load_lds_dwordx4 v[222:223], off
	v_lshl_add_u64 v[222:223], s[12:13], 0, v[180:181]
	s_mov_b32 m0, s35
	s_nop 0
	global_load_lds_dwordx4 v[222:223], off
	s_mov_b32 m0, s59
	s_nop 0
	global_load_lds_dwordx4 v[224:225], off
	s_waitcnt vmcnt(8)
	s_waitcnt lgkmcnt(0)
	s_barrier
	s_setprio 1
	s_waitcnt lgkmcnt(0)
	v_mfma_f32_16x16x32_bf16 v[52:55], v[72:75], v[160:163], v[52:55]
	v_mfma_f32_16x16x32_bf16 v[48:51], v[80:83], v[160:163], v[48:51]
	v_mfma_f32_16x16x32_bf16 v[44:47], v[72:75], v[168:171], v[44:47]
	v_mfma_f32_16x16x32_bf16 v[40:43], v[80:83], v[168:171], v[40:43]
	v_mfma_f32_16x16x32_bf16 v[28:31], v[72:75], v[202:205], v[28:31]
	v_mfma_f32_16x16x32_bf16 v[24:27], v[80:83], v[202:205], v[24:27]
	v_mfma_f32_16x16x32_bf16 v[60:63], v[72:75], v[210:213], v[60:63]
	v_mfma_f32_16x16x32_bf16 v[56:59], v[80:83], v[210:213], v[56:59]
	v_mfma_f32_16x16x32_bf16 v[52:55], v[76:79], v[164:167], v[52:55]
	v_mfma_f32_16x16x32_bf16 v[48:51], v[84:87], v[164:167], v[48:51]
	v_mfma_f32_16x16x32_bf16 v[44:47], v[76:79], v[172:175], v[44:47]
	v_mfma_f32_16x16x32_bf16 v[40:43], v[84:87], v[172:175], v[40:43]
	v_mfma_f32_16x16x32_bf16 v[28:31], v[76:79], v[206:209], v[28:31]
	v_mfma_f32_16x16x32_bf16 v[24:27], v[84:87], v[206:209], v[24:27]
	v_mfma_f32_16x16x32_bf16 v[60:63], v[76:79], v[214:217], v[60:63]
	v_mfma_f32_16x16x32_bf16 v[56:59], v[84:87], v[214:217], v[56:59]
	s_setprio 0
	s_setprio 1
	v_mfma_f32_16x16x32_bf16 v[36:39], v[104:107], v[160:163], v[36:39]
	v_mfma_f32_16x16x32_bf16 v[32:35], v[152:155], v[160:163], v[32:35]
	v_mfma_f32_16x16x32_bf16 v[20:23], v[104:107], v[168:171], v[20:23]
	v_mfma_f32_16x16x32_bf16 v[16:19], v[152:155], v[168:171], v[16:19]
	v_mfma_f32_16x16x32_bf16 v[12:15], v[104:107], v[202:205], v[12:15]
	v_mfma_f32_16x16x32_bf16 v[8:11], v[152:155], v[202:205], v[8:11]
	v_mfma_f32_16x16x32_bf16 v[4:7], v[104:107], v[210:213], v[4:7]
	v_mfma_f32_16x16x32_bf16 v[0:3], v[152:155], v[210:213], v[0:3]
	v_mfma_f32_16x16x32_bf16 v[36:39], v[108:111], v[164:167], v[36:39]
	v_mfma_f32_16x16x32_bf16 v[32:35], v[156:159], v[164:167], v[32:35]
	v_mfma_f32_16x16x32_bf16 v[20:23], v[108:111], v[172:175], v[20:23]
	v_mfma_f32_16x16x32_bf16 v[16:19], v[156:159], v[172:175], v[16:19]
	v_mfma_f32_16x16x32_bf16 v[12:15], v[108:111], v[206:209], v[12:15]
	v_mfma_f32_16x16x32_bf16 v[8:11], v[156:159], v[206:209], v[8:11]
	v_mfma_f32_16x16x32_bf16 v[4:7], v[108:111], v[214:217], v[4:7]
	v_mfma_f32_16x16x32_bf16 v[0:3], v[156:159], v[214:217], v[0:3]
	s_setprio 0
	s_barrier
	s_add_i32 s75, 0, 0x18000
	s_add_i32 s95, 0, 0x1c000
	v_add_u32_e32 v84, s75, v179
	v_add_u32_e32 v156, s95, v179
	ds_read_b128 v[72:75], v84
	ds_read_b128 v[76:79], v84 offset:1024
	ds_read_b128 v[80:83], v84 offset:2048
	ds_read_b128 v[84:87], v84 offset:3072
	ds_read_b128 v[104:107], v156
	ds_read_b128 v[108:111], v156 offset:1024
	ds_read_b128 v[152:155], v156 offset:2048
	ds_read_b128 v[156:159], v156 offset:3072
	s_add_u32 s12, s12, 0x80000
	s_addc_u32 s13, s13, 0
	s_mov_b32 m0, s76
	v_lshl_add_u64 v[226:227], s[12:13], 0, v[180:181]
	ds_read_b128 v[160:163], v234 offset:32768
	ds_read_b128 v[164:167], v234 offset:33792
	ds_read_b128 v[168:171], v234 offset:34816
	ds_read_b128 v[172:175], v234 offset:35840
	ds_read_b128 v[202:205], v234 offset:36864
	ds_read_b128 v[206:209], v234 offset:37888
	ds_read_b128 v[210:213], v234 offset:38912
	ds_read_b128 v[214:217], v234 offset:39936
	global_load_lds_dwordx4 v[226:227], off
	v_lshl_add_u64 v[226:227], s[12:13], 0, v[184:185]
	s_mov_b32 m0, s77
	s_nop 0
	global_load_lds_dwordx4 v[226:227], off
	s_waitcnt vmcnt(8)
	s_waitcnt lgkmcnt(0)
	s_barrier
; #define PG8_STAGE(bufoff, gbase, voff) do { _Pragma("unroll") for (int _i = 0; _i < 2; ++_i) \
;         __builtin_amdgcn_global_load_lds((const unsigned*)((const char*)(gbase) + (voff)[_i]), (LAS unsigned*)(lds + (bufoff) + ldsw + _i * 8192), 16, 0, 0); } while (0)
; #define PG8_LDA(dst, b, h) do { _Pragma("unroll") for (int m = 0; m < 4; ++m) _Pragma("unroll") for (int k = 0; k < 2; ++k) dst[m][k] = *(const LAS bf16x8*)(lds + PG8_SA(b, h) + aoff + m * 2048 + k * 1024); } while (0)
; #define PG8_MMA(ai, bj, At, Bt) do { __builtin_amdgcn_s_setprio(1); _Pragma("unroll") for (int m = 0; m < 4; ++m) _Pragma("unroll") for (int n = 0; n < 2; ++n) _Pragma("unroll") for (int k = 0; k < 2; ++k) \
;         acc[ai][bj][m][n] = __builtin_amdgcn_mfma_f32_16x16x32_bf16(Bt[n][k], At[m][k], acc[ai][bj][m][n], 0, 0, 0); __builtin_amdgcn_s_setprio(0); } while (0)
; #define PG8_WAIT_V(n) asm volatile("s_waitcnt vmcnt(" #n ")" ::: "memory")
; #define PG8_WAIT_L(n) asm volatile("s_waitcnt lgkmcnt(" #n ")" ::: "memory")
; #define PG8_BAR __builtin_amdgcn_s_barrier()
; #define PG8_SCHED __builtin_amdgcn_sched_barrier(0)
; template <class Epi>
; __device__ __forceinline__ void gemm_phase(LAS unsigned char* lds, const bf16_t* A0, const bf16_t* B0, const bf16_t* A1, const bf16_t* B1, const int K, const Order& S, const Epi& E) {
;     ...
;             PG8_WAIT_V(8); PG8_WAIT_L(0); PG8_BAR; PG8_MMA(0, 0, At, Bf0); PG8_MMA(0, 1, At, Bf1); PG8_BAR; PG8_SCHED;
;             PG8_LDA(At, 1, 1); PG8_STAGE(PG8_SB(1, 0), b3, voffB); PG8_STAGE(PG8_SB(1, 1), b3 + hstep, voffB); PG8_STAGE(PG8_SA(1, 0), a3, voffA);
;             PG8_WAIT_V(8); PG8_WAIT_L(0); PG8_BAR; PG8_MMA(1, 0, At, Bf0); PG8_MMA(1, 1, At, Bf1); PG8_BAR; PG8_SCHED;
;         }
;         if (wr == 0) PG8_BAR;
	s_setprio 1
	s_waitcnt lgkmcnt(0)
	v_mfma_f32_16x16x32_bf16 v[100:103], v[72:75], v[160:163], v[100:103]
	v_mfma_f32_16x16x32_bf16 v[96:99], v[80:83], v[160:163], v[96:99]
	v_mfma_f32_16x16x32_bf16 v[148:151], v[72:75], v[168:171], v[148:151]
	v_mfma_f32_16x16x32_bf16 v[144:147], v[80:83], v[168:171], v[144:147]
	v_mfma_f32_16x16x32_bf16 v[132:135], v[72:75], v[202:205], v[132:135]
	v_mfma_f32_16x16x32_bf16 v[128:131], v[80:83], v[202:205], v[128:131]
	v_mfma_f32_16x16x32_bf16 v[68:71], v[72:75], v[210:213], v[68:71]
	v_mfma_f32_16x16x32_bf16 v[64:67], v[80:83], v[210:213], v[64:67]
	v_mfma_f32_16x16x32_bf16 v[100:103], v[76:79], v[164:167], v[100:103]
	v_mfma_f32_16x16x32_bf16 v[96:99], v[84:87], v[164:167], v[96:99]
	v_mfma_f32_16x16x32_bf16 v[148:151], v[76:79], v[172:175], v[148:151]
	v_mfma_f32_16x16x32_bf16 v[144:147], v[84:87], v[172:175], v[144:147]
	v_mfma_f32_16x16x32_bf16 v[132:135], v[76:79], v[206:209], v[132:135]
	v_mfma_f32_16x16x32_bf16 v[128:131], v[84:87], v[206:209], v[128:131]
	v_mfma_f32_16x16x32_bf16 v[68:71], v[76:79], v[214:217], v[68:71]
	v_mfma_f32_16x16x32_bf16 v[64:67], v[84:87], v[214:217], v[64:67]
	s_setprio 0
	s_setprio 1
	v_mfma_f32_16x16x32_bf16 v[92:95], v[104:107], v[160:163], v[92:95]
	v_mfma_f32_16x16x32_bf16 v[88:91], v[152:155], v[160:163], v[88:91]
	v_mfma_f32_16x16x32_bf16 v[140:143], v[104:107], v[168:171], v[140:143]
	v_mfma_f32_16x16x32_bf16 v[136:139], v[152:155], v[168:171], v[136:139]
	v_mfma_f32_16x16x32_bf16 v[124:127], v[104:107], v[202:205], v[124:127]
	v_mfma_f32_16x16x32_bf16 v[120:123], v[152:155], v[202:205], v[120:123]
	v_mfma_f32_16x16x32_bf16 v[116:119], v[104:107], v[210:213], v[116:119]
	v_mfma_f32_16x16x32_bf16 v[112:115], v[152:155], v[210:213], v[112:115]
	v_mfma_f32_16x16x32_bf16 v[92:95], v[108:111], v[164:167], v[92:95]
	v_mfma_f32_16x16x32_bf16 v[88:91], v[156:159], v[164:167], v[88:91]
	v_mfma_f32_16x16x32_bf16 v[140:143], v[108:111], v[172:175], v[140:143]
	v_mfma_f32_16x16x32_bf16 v[136:139], v[156:159], v[172:175], v[136:139]
	v_mfma_f32_16x16x32_bf16 v[124:127], v[108:111], v[206:209], v[124:127]
	v_mfma_f32_16x16x32_bf16 v[120:123], v[156:159], v[206:209], v[120:123]
	v_mfma_f32_16x16x32_bf16 v[116:119], v[108:111], v[214:217], v[116:119]
	v_mfma_f32_16x16x32_bf16 v[112:115], v[156:159], v[214:217], v[112:115]
	s_setprio 0
	s_barrier
	s_add_i32 s12, s75, s33
	v_lshl_add_u64 v[218:219], v[218:219], 0, s[42:43]
	s_mov_b32 m0, s12
	ds_read_b128 v[160:163], v234 offset:49152
	ds_read_b128 v[164:167], v234 offset:50176
	ds_read_b128 v[168:171], v234 offset:51200
	ds_read_b128 v[172:175], v234 offset:52224
	ds_read_b128 v[202:205], v234 offset:53248
	ds_read_b128 v[206:209], v234 offset:54272
	ds_read_b128 v[210:213], v234 offset:55296
	ds_read_b128 v[214:217], v234 offset:56320
	global_load_lds_dwordx4 v[218:219], off
	s_add_i32 m0, s12, 0x2000
	s_add_u32 s10, s10, 0x80080
	v_lshl_add_u64 v[218:219], v[220:221], 0, s[42:43]
	s_addc_u32 s11, s11, 0
	s_add_i32 s12, s95, s33
	global_load_lds_dwordx4 v[218:219], off
	v_lshl_add_u64 v[218:219], s[10:11], 0, v[182:183]
	s_mov_b32 m0, s12
	s_nop 0
	global_load_lds_dwordx4 v[218:219], off
	v_lshl_add_u64 v[218:219], s[10:11], 0, v[186:187]
	s_add_i32 m0, s12, 0x2000
	s_nop 0
	global_load_lds_dwordx4 v[218:219], off
	v_lshl_add_u64 v[218:219], v[222:223], 0, s[42:43]
	s_mov_b32 m0, s80
	s_nop 0
	global_load_lds_dwordx4 v[218:219], off
	v_lshl_add_u64 v[218:219], v[224:225], 0, s[42:43]
	s_mov_b32 m0, s81
	s_nop 0
	global_load_lds_dwordx4 v[218:219], off
	s_waitcnt vmcnt(8)
	s_waitcnt lgkmcnt(0)
	s_barrier
	s_setprio 1
	s_waitcnt lgkmcnt(0)
	v_mfma_f32_16x16x32_bf16 v[52:55], v[72:75], v[160:163], v[52:55]
	v_mfma_f32_16x16x32_bf16 v[48:51], v[80:83], v[160:163], v[48:51]
	v_mfma_f32_16x16x32_bf16 v[44:47], v[72:75], v[168:171], v[44:47]
	v_mfma_f32_16x16x32_bf16 v[40:43], v[80:83], v[168:171], v[40:43]
	v_mfma_f32_16x16x32_bf16 v[28:31], v[72:75], v[202:205], v[28:31]
	v_mfma_f32_16x16x32_bf16 v[24:27], v[80:83], v[202:205], v[24:27]
	v_mfma_f32_16x16x32_bf16 v[60:63], v[72:75], v[210:213], v[60:63]
	v_mfma_f32_16x16x32_bf16 v[56:59], v[80:83], v[210:213], v[56:59]
	v_mfma_f32_16x16x32_bf16 v[52:55], v[76:79], v[164:167], v[52:55]
	v_mfma_f32_16x16x32_bf16 v[48:51], v[84:87], v[164:167], v[48:51]
	v_mfma_f32_16x16x32_bf16 v[44:47], v[76:79], v[172:175], v[44:47]
	v_mfma_f32_16x16x32_bf16 v[40:43], v[84:87], v[172:175], v[40:43]
	v_mfma_f32_16x16x32_bf16 v[28:31], v[76:79], v[206:209], v[28:31]
	v_mfma_f32_16x16x32_bf16 v[24:27], v[84:87], v[206:209], v[24:27]
	v_mfma_f32_16x16x32_bf16 v[60:63], v[76:79], v[214:217], v[60:63]
	v_mfma_f32_16x16x32_bf16 v[56:59], v[84:87], v[214:217], v[56:59]
	s_setprio 0
	s_setprio 1
	v_mfma_f32_16x16x32_bf16 v[36:39], v[104:107], v[160:163], v[36:39]
	v_mfma_f32_16x16x32_bf16 v[32:35], v[152:155], v[160:163], v[32:35]
	v_mfma_f32_16x16x32_bf16 v[20:23], v[104:107], v[168:171], v[20:23]
	v_mfma_f32_16x16x32_bf16 v[16:19], v[152:155], v[168:171], v[16:19]
	v_mfma_f32_16x16x32_bf16 v[12:15], v[104:107], v[202:205], v[12:15]
	v_mfma_f32_16x16x32_bf16 v[8:11], v[152:155], v[202:205], v[8:11]
	v_mfma_f32_16x16x32_bf16 v[4:7], v[104:107], v[210:213], v[4:7]
	v_mfma_f32_16x16x32_bf16 v[0:3], v[152:155], v[210:213], v[0:3]
	v_mfma_f32_16x16x32_bf16 v[36:39], v[108:111], v[164:167], v[36:39]
	v_mfma_f32_16x16x32_bf16 v[32:35], v[156:159], v[164:167], v[32:35]
	v_mfma_f32_16x16x32_bf16 v[20:23], v[108:111], v[172:175], v[20:23]
	v_mfma_f32_16x16x32_bf16 v[16:19], v[156:159], v[172:175], v[16:19]
	v_mfma_f32_16x16x32_bf16 v[12:15], v[108:111], v[206:209], v[12:15]
	v_mfma_f32_16x16x32_bf16 v[8:11], v[156:159], v[206:209], v[8:11]
	v_mfma_f32_16x16x32_bf16 v[4:7], v[108:111], v[214:217], v[4:7]
	v_mfma_f32_16x16x32_bf16 v[0:3], v[156:159], v[214:217], v[0:3]
	s_setprio 0
	s_barrier
	s_add_i32 s74, s74, 2
	s_add_u32 s8, s8, 0x100
	s_addc_u32 s9, s9, 0
	s_add_u32 s72, s72, 0x100
	s_addc_u32 s73, s73, 0
	s_cmp_gt_u32 s74, 29
	s_cbranch_scc0 .LBB0_1154
	s_and_b64 vcc, exec, s[44:45]
	s_cbranch_vccz .LBB0_1157
	s_barrier
; #define LAS __attribute__((address_space(3)))
; #define EPI_BAR() do { asm volatile("s_waitcnt lgkmcnt(0)" ::: "memory"); __builtin_amdgcn_s_barrier(); asm volatile("" ::: "memory"); } while (0)
; #define FOR_AI_M _Pragma("unroll") for (int ai = 0; ai < 2; ++ai) _Pragma("unroll") for (int m = 0; m < 4; ++m)
; #define FOR_BJ _Pragma("unroll") for (int bj = 0; bj < 2; ++bj)
;     __device__ __forceinline__ void operator()(f32x4 (&acc)[2][2][4][2], const Unit& u, int wr, int wc, int fr, int fq) const {
;     ...
;         FOR_AI_M { const int grow = u.pm * BM + ai * HALF + wr * 64 + m * 16 + fr;
;             const f32x4 a0 = *(const f32x4*)(SS3 + (size_t)grow * 8), a1 = *(const f32x4*)(SS3 + (size_t)grow * 8 + 4);
;             const float r3 = rsqrtf(((a0[0] + a0[1]) + (a0[2] + a0[3]) + (a1[0] + a1[1]) + (a1[2] + a1[3])) * (1.f / 2048.f) + EPS);
;             FOR_BJ { acc[ai][bj][m][0] *= r3; acc[ai][bj][m][1] *= r3; } }
;         if (fr >= 14) {
; #pragma unroll
;             for (int ai = 0; ai < 2; ++ai) { LAS float* xp = XH + ((2 * ai + wr) * 2 + (fr - 14)) * 128 + 32 * wc + 8 * fq; *(LAS f32x4*)xp = acc[ai][0][3][0]; *(LAS f32x4*)(xp + 4) = acc[ai][0][3][1]; } }
;         EPI_BAR();
.LBB0_1157:
	s_mov_b32 s98, 0xbfb8aa3b
	s_lshl_b32 s61, s70, 8
	s_add_i32 s63, s61, s79
	v_or_b32_e32 v220, s63, v190
	v_ashrrev_i32_e32 v221, 31, v220
	v_lshlrev_b64 v[72:73], 5, v[220:221]
	v_or_b32_e32 v216, 16, v220
	s_waitcnt vmcnt(0)
	v_lshl_add_u64 v[72:73], s[86:87], 0, v[72:73]
	v_ashrrev_i32_e32 v217, 31, v216
	global_load_dwordx4 v[152:155], v[72:73], off offset:16
	global_load_dwordx4 v[156:159], v[72:73], off
	v_lshlrev_b64 v[72:73], 5, v[216:217]
	v_or_b32_e32 v212, 32, v220
	v_lshl_add_u64 v[72:73], s[86:87], 0, v[72:73]
	v_ashrrev_i32_e32 v213, 31, v212
	global_load_dwordx4 v[104:107], v[72:73], off offset:16
	global_load_dwordx4 v[108:111], v[72:73], off
	v_lshlrev_b64 v[72:73], 5, v[212:213]
	v_lshl_add_u64 v[76:77], s[86:87], 0, v[72:73]
	global_load_dwordx4 v[72:75], v[76:77], off offset:16
	s_nop 0
	global_load_dwordx4 v[76:79], v[76:77], off
	v_or_b32_e32 v210, 48, v220
	v_ashrrev_i32_e32 v211, 31, v210
	v_lshlrev_b64 v[252:253], 5, v[210:211]
	v_lshl_add_u64 v[252:253], s[86:87], 0, v[252:253]
	global_load_dwordx4 v[244:247], v[252:253], off offset:16
	global_load_dwordx4 v[248:251], v[252:253], off
	s_mov_b32 s8, 0x358637bd
	v_mov_b64_e32 v[164:165], s[8:9]
	v_add_u32_e32 v208, 0x80, v220
	v_ashrrev_i32_e32 v209, 31, v208
	v_add_u32_e32 v204, 0x90, v220
	v_add_u32_e32 v206, 0xa0, v220
	v_ashrrev_i32_e32 v205, 31, v204
	v_ashrrev_i32_e32 v207, 31, v206
	v_lshlrev_b64 v[160:161], 5, v[206:207]
	v_lshl_add_u64 v[166:167], s[86:87], 0, v[160:161]
	v_add_u32_e32 v202, 0xb0, v220
	v_ashrrev_i32_e32 v203, 31, v202
	s_waitcnt vmcnt(0)
	v_mov_b32_e32 v80, v77
	v_mov_b32_e32 v81, v78
	v_mov_b32_e32 v77, v79
	v_pk_add_f32 v[80:81], v[80:81], v[76:77]
	v_mov_b32_e32 v76, v74
	v_mov_b32_e32 v77, v72
	v_mov_b32_e32 v72, v75
	v_pk_add_f32 v[82:83], v[76:77], v[72:73]
	v_mov_b64_e32 v[72:73], v[244:245]
	v_mov_b64_e32 v[74:75], v[246:247]
	v_mov_b64_e32 v[76:77], v[248:249]
	v_mov_b64_e32 v[78:79], v[250:251]
	global_load_dwordx4 v[160:163], v[166:167], off offset:16
	s_nop 0
	global_load_dwordx4 v[166:169], v[166:167], off
	v_lshlrev_b64 v[252:253], 5, v[202:203]
	v_lshl_add_u64 v[252:253], s[86:87], 0, v[252:253]
	global_load_dwordx4 v[244:247], v[252:253], off offset:16
	global_load_dwordx4 v[248:251], v[252:253], off
	v_mov_b32_e32 v84, v77
	v_mov_b32_e32 v85, v78
	v_mov_b32_e32 v77, v79
	v_pk_add_f32 v[76:77], v[84:85], v[76:77]
	v_mov_b32_e32 v78, v74
	v_mov_b32_e32 v79, v72
	v_mov_b32_e32 v72, v75
	v_pk_add_f32 v[72:73], v[78:79], v[72:73]
	v_mov_b32_e32 v74, v76
	v_mov_b32_e32 v75, v80
	v_mov_b32_e32 v80, v77
	v_pk_add_f32 v[74:75], v[74:75], v[80:81]
	v_mov_b32_e32 v76, v73
	v_mov_b32_e32 v77, v83
	v_pk_add_f32 v[74:75], v[74:75], v[76:77]
	v_mov_b32_e32 v73, v82
	v_pk_add_f32 v[72:73], v[72:73], v[74:75]
	s_nop 0
	v_pk_fma_f32 v[214:215], v[72:73], s[58:59], v[164:165] op_sel_hi:[1,0,0]
	s_nop 0
	v_cmp_gt_f32_e32 vcc, s85, v214
	v_mul_f32_e32 v72, 0x4b800000, v214
	v_cmp_gt_f32_e64 s[12:13], s85, v215
	v_cndmask_b32_e32 v72, v214, v72, vcc
	v_rsq_f32_e32 v72, v72
	s_nop 0
	v_mul_f32_e32 v73, 0x45800000, v72
	v_cndmask_b32_e32 v224, v72, v73, vcc
	v_pk_mul_f32 v[80:81], v[64:65], v[224:225] op_sel_hi:[1,0]
	v_lshlrev_b64 v[64:65], 5, v[208:209]
	v_lshl_add_u64 v[64:65], s[86:87], 0, v[64:65]
	global_load_dwordx4 v[72:75], v[64:65], off offset:16
	global_load_dwordx4 v[76:79], v[64:65], off
	v_lshlrev_b64 v[64:65], 5, v[204:205]
	v_pk_mul_f32 v[84:85], v[68:69], v[224:225] op_sel_hi:[1,0]
	v_lshl_add_u64 v[68:69], s[86:87], 0, v[64:65]
	v_pk_mul_f32 v[86:87], v[70:71], v[224:225] op_sel_hi:[1,0]
	v_pk_mul_f32 v[82:83], v[66:67], v[224:225] op_sel_hi:[1,0]
	global_load_dwordx4 v[64:67], v[68:69], off offset:16
	s_nop 0
	global_load_dwordx4 v[68:71], v[68:69], off
	s_nop 0
	s_waitcnt vmcnt(4)
	v_mov_b32_e32 v170, v167
	v_mov_b32_e32 v171, v168
	v_mov_b32_e32 v167, v169
	v_pk_add_f32 v[168:169], v[170:171], v[166:167]
	v_mov_b32_e32 v166, v162
	v_mov_b32_e32 v167, v160
	v_mov_b32_e32 v160, v163
	v_pk_add_f32 v[166:167], v[166:167], v[160:161]
	v_mov_b64_e32 v[160:161], v[244:245]
	v_mov_b64_e32 v[162:163], v[246:247]
	v_mov_b64_e32 v[170:171], v[248:249]
	v_mov_b64_e32 v[172:173], v[250:251]
	v_mov_b32_e32 v174, v171
	v_mov_b32_e32 v175, v172
	v_mov_b32_e32 v171, v173
	v_pk_add_f32 v[170:171], v[174:175], v[170:171]
	v_mov_b32_e32 v172, v162
	v_mov_b32_e32 v173, v160
	v_mov_b32_e32 v160, v163
	v_pk_add_f32 v[160:161], v[172:173], v[160:161]
	v_mov_b32_e32 v162, v170
	v_mov_b32_e32 v163, v168
	v_mov_b32_e32 v168, v171
	v_pk_add_f32 v[162:163], v[162:163], v[168:169]
	v_mov_b32_e32 v168, v161
	v_mov_b32_e32 v169, v167
	v_pk_add_f32 v[162:163], v[162:163], v[168:169]
	v_mov_b32_e32 v161, v166
	v_pk_add_f32 v[160:161], v[160:161], v[162:163]
	s_nop 0
	v_pk_fma_f32 v[218:219], v[160:161], s[58:59], v[164:165] op_sel_hi:[1,0,0]
	s_nop 0
	v_cmp_gt_f32_e32 vcc, s85, v218
	v_mul_f32_e32 v160, 0x4b800000, v218
	v_cmp_gt_f32_e64 s[8:9], s85, v219
	v_cndmask_b32_e32 v160, v218, v160, vcc
	v_rsq_f32_e32 v160, v160
	s_nop 0
	v_mul_f32_e32 v161, 0x45800000, v160
	v_cndmask_b32_e32 v214, v160, v161, vcc
	v_pk_mul_f32 v[62:63], v[62:63], v[214:215] op_sel_hi:[1,0]
	v_pk_mul_f32 v[60:61], v[60:61], v[214:215] op_sel_hi:[1,0]
	v_pk_mul_f32 v[58:59], v[58:59], v[214:215] op_sel_hi:[1,0]
	v_pk_mul_f32 v[56:57], v[56:57], v[214:215] op_sel_hi:[1,0]
	s_and_saveexec_b64 s[10:11], s[48:49]
	s_cbranch_execz .LBB0_1159
	ds_write_b128 v195, v[84:87]
	ds_write_b128 v195, v[80:83] offset:16
	ds_write_b128 v191, v[60:63]
	ds_write_b128 v191, v[56:59] offset:16
.LBB0_1159:
	s_or_b64 exec, exec, s[10:11]
	s_waitcnt vmcnt(0)
	s_waitcnt lgkmcnt(0)
	s_barrier
	s_cmpk_lt_i32 s70, 0x80
	s_cselect_b64 s[72:73], -1, 0
	s_cmpk_gt_i32 s70, 0x7f
	s_mov_b64 s[10:11], -1
	s_cbranch_scc1 .LBB0_1163
	v_and_b32_e32 v162, 0x1fff, v210
	s_movk_i32 s1, 0x1ffd
	v_cmp_lt_u32_e32 vcc, s1, v162
	v_mov_b64_e32 v[160:161], 0
	s_and_saveexec_b64 s[10:11], vcc
	s_ashr_i32 s74, s63, 13
	s_ashr_i32 s75, s74, 31
	v_add_u32_e32 v188, 0xffffe002, v162
	v_lshl_add_u64 v[162:163], s[74:75], 1, v[188:189]
	v_mov_b64_e32 v[160:161], s[38:39]
	v_mad_u64_u32 v[160:161], s[74:75], v162, s52, v[160:161]
	v_mad_i32_i24 v161, v163, s52, v161
	s_or_b64 exec, exec, s[10:11]
	s_mov_b64 s[10:11], 0

; __device__ __forceinline__ u32x4 pack8(f32x4 a, f32x4 b) { u32x4 w; w.x = cvtpk(a[0], a[1]); w.y = cvtpk(a[2], a[3]); w.z = cvtpk(b[0], b[1]); w.w = cvtpk(b[2], b[3]); return w; }
; #define FOR_BJ _Pragma("unroll") for (int bj = 0; bj < 2; ++bj)
; __device__ __forceinline__ float dpp_ror1(float v) { return __builtin_bit_cast(float, __builtin_amdgcn_update_dpp(0, __builtin_bit_cast(int, v), 0x121, 0xf, 0xf, false)); }
; __device__ __forceinline__ float dpp_ror2(float v) { return __builtin_bit_cast(float, __builtin_amdgcn_update_dpp(0, __builtin_bit_cast(int, v), 0x122, 0xf, 0xf, false)); }
; __device__ __forceinline__ float silu_mul(float cv, float g) { return cv * __builtin_amdgcn_rcpf(1.f + __builtin_amdgcn_exp2f(-cv * LOG2E)) * g; }
;     __device__ __forceinline__ void operator()(f32x4 (&acc)[2][2][4][2], const Unit& u, int wr, int wc, int fr, int fq) const {
;     ...
;             FOR_BJ { acc[ai][bj][m][0] *= r3; acc[ai][bj][m][1] *= r3; } }
;     ...
;             for (int m = 0; m < 4; ++m) {
;                 const int grow = u.pm * BM + ai * HALF + wr * 64 + m * 16 + fr;
;                 f32x4 av[2];
; #pragma unroll
;                 for (int n = 0; n < 2; ++n)
; #pragma unroll
;                     for (int e = 0; e < 4; ++e) {
;                         const float cur = acc[ai][0][m][n][e], prv = pv[n][e];
;                         const float a1 = dpp_ror1(cur), b1 = dpp_ror1(prv), a2 = dpp_ror2(cur), b2 = dpp_ror2(prv);
;                         const float p1 = fr >= 1 ? a1 : b1, p2 = fr >= 2 ? a2 : b2;
;                         const float cv = w0[n][e] * p2 + w1[n][e] * p1 + w2[n][e] * cur;
;                         av[n][e] = silu_mul(cv, acc[ai][1][m][n][e]);
;                     }
;                 *(u32x4*)(ACT + (size_t)grow * DFF + f0) = pack8(av[0], av[1]);
;                 pv[0] = acc[ai][0][m][0]; pv[1] = acc[ai][0][m][1];
.LBB0_1187:
	v_mul_f32_e32 v188, 0x4b800000, v226
	v_cndmask_b32_e64 v188, v226, v188, s[0:1]
	v_rsq_f32_e32 v188, v188
	v_mov_b32_e32 v225, v224
	v_mov_b32_e32 v205, 0
	s_and_b64 vcc, exec, s[10:11]
	v_mul_f32_e32 v203, 0x45800000, v188
	v_cndmask_b32_e64 v188, v188, v203, s[0:1]
	v_pk_mul_f32 v[228:229], v[148:149], v[188:189] op_sel_hi:[1,0]
	v_pk_mul_f32 v[148:149], v[142:143], v[188:189] op_sel_hi:[1,0]
	v_pk_mul_f32 v[142:143], v[136:137], v[188:189] op_sel_hi:[1,0]
	v_mul_f32_e32 v136, 0x4b800000, v215
	v_cndmask_b32_e64 v136, v215, v136, s[12:13]
	v_rsq_f32_e32 v136, v136
	v_pk_mul_f32 v[150:151], v[150:151], v[188:189] op_sel_hi:[1,0]
	v_pk_mul_f32 v[146:147], v[146:147], v[188:189] op_sel_hi:[1,0]
	v_pk_mul_f32 v[144:145], v[144:145], v[188:189] op_sel_hi:[1,0]
	v_mul_f32_e32 v137, 0x45800000, v136
	v_pk_mul_f32 v[226:227], v[140:141], v[188:189] op_sel_hi:[1,0]
	v_pk_mul_f32 v[140:141], v[138:139], v[188:189] op_sel_hi:[1,0]
	v_cndmask_b32_e64 v188, v136, v137, s[12:13]
	v_pk_mul_f32 v[136:137], v[124:125], v[188:189] op_sel_hi:[1,0]
	v_mov_b32_e32 v124, v224
	v_mov_b32_e32 v125, v224
	v_pk_mul_f32 v[138:139], v[132:133], v[188:189] op_sel_hi:[1,0]
	v_pk_mul_f32 v[132:133], v[126:127], v[188:189] op_sel_hi:[1,0]
	v_pk_mul_f32 v[126:127], v[120:121], v[188:189] op_sel_hi:[1,0]
	v_pk_mul_f32 v[118:119], v[118:119], v[124:125]
	v_pk_mul_f32 v[120:121], v[116:117], v[224:225]
	v_pk_mul_f32 v[114:115], v[114:115], v[124:125]
	v_pk_mul_f32 v[116:117], v[112:113], v[224:225]
	v_pk_mul_f32 v[134:135], v[134:135], v[188:189] op_sel_hi:[1,0]
	v_pk_mul_f32 v[130:131], v[130:131], v[188:189] op_sel_hi:[1,0]
	v_pk_mul_f32 v[128:129], v[128:129], v[188:189] op_sel_hi:[1,0]
	v_pk_mul_f32 v[122:123], v[122:123], v[188:189] op_sel_hi:[1,0]
	s_waitcnt vmcnt(1) lgkmcnt(1)
	v_mov_b32_dpp v112, v172 row_ror:1 row_mask:0xf bank_mask:0xf
	v_mov_b32_dpp v203, v164 row_ror:2 row_mask:0xf bank_mask:0xf
	v_mov_b32_dpp v124, v172 row_ror:2 row_mask:0xf bank_mask:0xf
	v_mov_b32_dpp v205, v165 row_ror:2 row_mask:0xf bank_mask:0xf
	v_mov_b32_dpp v125, v173 row_ror:2 row_mask:0xf bank_mask:0xf
	v_mov_b32_dpp v188, v164 row_ror:1 row_mask:0xf bank_mask:0xf
	v_mov_b32_dpp v172, v165 row_ror:1 row_mask:0xf bank_mask:0xf
	v_mov_b32_dpp v113, v173 row_ror:1 row_mask:0xf bank_mask:0xf
	v_cndmask_b32_e64 v125, v125, v205, s[6:7]
	v_cndmask_b32_e64 v124, v124, v203, s[6:7]
	v_cndmask_b32_e64 v113, v172, v113, s[4:5]
	v_cndmask_b32_e64 v112, v188, v112, s[4:5]
	v_pk_mul_f32 v[124:125], v[100:101], v[124:125]
	v_pk_fma_f32 v[112:113], v[104:105], v[112:113], v[124:125]
	s_waitcnt vmcnt(0)
	v_pk_fma_f32 v[112:113], v[164:165], v[108:109], v[112:113]
	v_pk_mul_f32 v[124:125], v[112:113], s[98:99] op_sel_hi:[1,0]
	v_exp_f32_e32 v124, v124
	v_exp_f32_e32 v125, v125
	v_mov_b32_dpp v165, v166 row_ror:2 row_mask:0xf bank_mask:0xf
	v_pk_add_f32 v[124:125], v[124:125], 1.0 op_sel_hi:[1,0]
	v_rcp_f32_e32 v124, v124
	v_rcp_f32_e32 v125, v125
	v_mov_b32_dpp v164, v166 row_ror:1 row_mask:0xf bank_mask:0xf
	v_mov_b32_dpp v173, v167 row_ror:1 row_mask:0xf bank_mask:0xf
	v_pk_mul_f32 v[112:113], v[112:113], v[124:125]
	s_nop 0
	v_pk_mul_f32 v[112:113], v[160:161], v[112:113]
	v_mov_b32_dpp v124, v174 row_ror:1 row_mask:0xf bank_mask:0xf
	v_mov_b32_dpp v160, v174 row_ror:2 row_mask:0xf bank_mask:0xf
	v_mov_b32_dpp v161, v175 row_ror:2 row_mask:0xf bank_mask:0xf
	v_mov_b32_dpp v174, v167 row_ror:2 row_mask:0xf bank_mask:0xf
	v_mov_b32_dpp v125, v175 row_ror:1 row_mask:0xf bank_mask:0xf
	v_cndmask_b32_e64 v161, v161, v174, s[6:7]
	v_cndmask_b32_e64 v160, v160, v165, s[6:7]
	v_cndmask_b32_e64 v125, v173, v125, s[4:5]
	v_cndmask_b32_e64 v124, v164, v124, s[4:5]
	v_pk_mul_f32 v[160:161], v[102:103], v[160:161]
	v_pk_fma_f32 v[124:125], v[106:107], v[124:125], v[160:161]
	s_nop 0
	v_pk_fma_f32 v[124:125], v[166:167], v[110:111], v[124:125]
	v_pk_mul_f32 v[160:161], v[124:125], s[98:99] op_sel_hi:[1,0]
	v_exp_f32_e32 v160, v160
	v_exp_f32_e32 v161, v161
	v_mov_b32_dpp v167, v156 row_ror:2 row_mask:0xf bank_mask:0xf
	v_pk_add_f32 v[160:161], v[160:161], 1.0 op_sel_hi:[1,0]
	v_rcp_f32_e32 v160, v160
	v_rcp_f32_e32 v161, v161
	v_mov_b32_dpp v175, v157 row_ror:2 row_mask:0xf bank_mask:0xf
	v_mov_b32_dpp v166, v156 row_ror:1 row_mask:0xf bank_mask:0xf
	v_pk_mul_f32 v[124:125], v[124:125], v[160:161]
	s_nop 0
	v_pk_mul_f32 v[124:125], v[162:163], v[124:125]
	s_waitcnt lgkmcnt(0)
; __device__ __forceinline__ u32x4 pack8(f32x4 a, f32x4 b) { u32x4 w; w.x = cvtpk(a[0], a[1]); w.y = cvtpk(a[2], a[3]); w.z = cvtpk(b[0], b[1]); w.w = cvtpk(b[2], b[3]); return w; }
; __device__ __forceinline__ float dpp_ror1(float v) { return __builtin_bit_cast(float, __builtin_amdgcn_update_dpp(0, __builtin_bit_cast(int, v), 0x121, 0xf, 0xf, false)); }
; __device__ __forceinline__ float dpp_ror2(float v) { return __builtin_bit_cast(float, __builtin_amdgcn_update_dpp(0, __builtin_bit_cast(int, v), 0x122, 0xf, 0xf, false)); }
; __device__ __forceinline__ float silu_mul(float cv, float g) { return cv * __builtin_amdgcn_rcpf(1.f + __builtin_amdgcn_exp2f(-cv * LOG2E)) * g; }
;     __device__ __forceinline__ void operator()(f32x4 (&acc)[2][2][4][2], const Unit& u, int wr, int wc, int fr, int fq) const {
;     ...
;             for (int m = 0; m < 4; ++m) {
;                 const int grow = u.pm * BM + ai * HALF + wr * 64 + m * 16 + fr;
;                 f32x4 av[2];
; #pragma unroll
;                 for (int n = 0; n < 2; ++n)
; #pragma unroll
;                     for (int e = 0; e < 4; ++e) {
;                         const float cur = acc[ai][0][m][n][e], prv = pv[n][e];
;                         const float a1 = dpp_ror1(cur), b1 = dpp_ror1(prv), a2 = dpp_ror2(cur), b2 = dpp_ror2(prv);
;                         const float p1 = fr >= 1 ? a1 : b1, p2 = fr >= 2 ? a2 : b2;
;                         const float cv = w0[n][e] * p2 + w1[n][e] * p1 + w2[n][e] * cur;
;                         av[n][e] = silu_mul(cv, acc[ai][1][m][n][e]);
;                     }
;                 *(u32x4*)(ACT + (size_t)grow * DFF + f0) = pack8(av[0], av[1]);
;                 pv[0] = acc[ai][0][m][0]; pv[1] = acc[ai][0][m][1];
	v_mov_b32_dpp v160, v168 row_ror:1 row_mask:0xf bank_mask:0xf
	v_mov_b32_dpp v162, v168 row_ror:2 row_mask:0xf bank_mask:0xf
	v_mov_b32_dpp v163, v169 row_ror:2 row_mask:0xf bank_mask:0xf
	v_mov_b32_dpp v168, v157 row_ror:1 row_mask:0xf bank_mask:0xf
	v_mov_b32_dpp v161, v169 row_ror:1 row_mask:0xf bank_mask:0xf
	v_cndmask_b32_e64 v163, v163, v175, s[6:7]
	v_cndmask_b32_e64 v162, v162, v167, s[6:7]
	v_cndmask_b32_e64 v161, v168, v161, s[4:5]
	v_cndmask_b32_e64 v160, v166, v160, s[4:5]
	v_pk_mul_f32 v[162:163], v[88:89], v[162:163]
	v_pk_fma_f32 v[160:161], v[92:93], v[160:161], v[162:163]
	v_pk_fma_f32 v[156:157], v[156:157], v[96:97], v[160:161]
	v_pk_mul_f32 v[160:161], v[156:157], s[98:99] op_sel_hi:[1,0]
	v_exp_f32_e32 v160, v160
	v_exp_f32_e32 v161, v161
	v_mov_b32_dpp v163, v158 row_ror:2 row_mask:0xf bank_mask:0xf
	v_mov_b32_dpp v162, v158 row_ror:1 row_mask:0xf bank_mask:0xf
	v_pk_add_f32 v[160:161], v[160:161], 1.0 op_sel_hi:[1,0]
	v_rcp_f32_e32 v160, v160
	v_rcp_f32_e32 v161, v161
	v_mov_b32_dpp v169, v159 row_ror:1 row_mask:0xf bank_mask:0xf
	v_pk_mul_f32 v[156:157], v[156:157], v[160:161]
	s_nop 0
	v_pk_mul_f32 v[156:157], v[152:153], v[156:157]
	v_mov_b32_dpp v152, v170 row_ror:1 row_mask:0xf bank_mask:0xf
	v_mov_b32_dpp v160, v170 row_ror:2 row_mask:0xf bank_mask:0xf
	v_mov_b32_dpp v161, v171 row_ror:2 row_mask:0xf bank_mask:0xf
	v_mov_b32_dpp v170, v159 row_ror:2 row_mask:0xf bank_mask:0xf
	v_mov_b32_dpp v153, v171 row_ror:1 row_mask:0xf bank_mask:0xf
	v_cndmask_b32_e64 v161, v161, v170, s[6:7]
	v_cndmask_b32_e64 v160, v160, v163, s[6:7]
	v_cndmask_b32_e64 v153, v169, v153, s[4:5]
	v_cndmask_b32_e64 v152, v162, v152, s[4:5]
	v_pk_mul_f32 v[160:161], v[90:91], v[160:161]
	v_pk_fma_f32 v[152:153], v[94:95], v[152:153], v[160:161]
	v_pk_fma_f32 v[152:153], v[158:159], v[98:99], v[152:153]
	v_pk_mul_f32 v[158:159], v[152:153], s[98:99] op_sel_hi:[1,0]
	v_exp_f32_e32 v158, v158
	v_exp_f32_e32 v159, v159
	v_mov_b32_dpp v161, v229 row_ror:2 row_mask:0xf bank_mask:0xf
	v_mov_b32_dpp v160, v229 row_ror:1 row_mask:0xf bank_mask:0xf
	v_pk_add_f32 v[158:159], v[158:159], 1.0 op_sel_hi:[1,0]
	v_rcp_f32_e32 v158, v158
	v_rcp_f32_e32 v159, v159
	v_mov_b32_dpp v171, v150 row_ror:1 row_mask:0xf bank_mask:0xf
	v_pk_mul_f32 v[152:153], v[152:153], v[158:159]
	s_nop 0
	v_pk_mul_f32 v[158:159], v[154:155], v[152:153]
	v_cvt_pk_bf16_f32 v153, v124, v125
	v_mov_b64_e32 v[124:125], s[14:15]
	v_cvt_pk_bf16_f32 v152, v112, v113
	v_cvt_pk_bf16_f32 v154, v156, v157
	v_cvt_pk_bf16_f32 v155, v158, v159
	v_mad_i64_i32 v[156:157], s[0:1], v220, s94, v[124:125]
	v_lshlrev_b64 v[112:113], 1, v[222:223]
	v_lshl_add_u64 v[156:157], v[156:157], 0, v[112:113]
	v_mov_b32_dpp v159, v228 row_ror:2 row_mask:0xf bank_mask:0xf
	global_store_dwordx4 v[156:157], v[152:155], off
	v_mov_b32_dpp v158, v228 row_ror:1 row_mask:0xf bank_mask:0xf
	s_nop 0
	v_cndmask_b32_e64 v155, v205, v161, s[6:7]
	v_cndmask_b32_e64 v154, v203, v159, s[6:7]
	v_cndmask_b32_e64 v153, v160, v172, s[4:5]
	v_cndmask_b32_e64 v152, v158, v188, s[4:5]
	v_pk_mul_f32 v[154:155], v[100:101], v[154:155]
	v_pk_fma_f32 v[152:153], v[104:105], v[152:153], v[154:155]
	v_pk_fma_f32 v[152:153], v[228:229], v[108:109], v[152:153]
	v_mov_b32_dpp v172, v150 row_ror:2 row_mask:0xf bank_mask:0xf
	v_pk_mul_f32 v[154:155], v[152:153], s[98:99] op_sel_hi:[1,0]
	v_exp_f32_e32 v154, v154
	v_exp_f32_e32 v155, v155
	v_mov_b32_dpp v203, v151 row_ror:2 row_mask:0xf bank_mask:0xf
	v_pk_add_f32 v[154:155], v[154:155], 1.0 op_sel_hi:[1,0]
	v_rcp_f32_e32 v154, v154
	v_rcp_f32_e32 v155, v155
	v_mov_b32_dpp v188, v151 row_ror:1 row_mask:0xf bank_mask:0xf
	v_cndmask_b32_e64 v157, v174, v203, s[6:7]
	v_cndmask_b32_e64 v156, v165, v172, s[6:7]
	v_pk_mul_f32 v[152:153], v[152:153], v[154:155]
	v_cndmask_b32_e64 v155, v188, v173, s[4:5]
	v_cndmask_b32_e64 v154, v171, v164, s[4:5]
	v_pk_mul_f32 v[156:157], v[102:103], v[156:157]
	v_pk_fma_f32 v[154:155], v[106:107], v[154:155], v[156:157]
	v_pk_fma_f32 v[150:151], v[150:151], v[110:111], v[154:155]
	v_pk_mul_f32 v[154:155], v[150:151], s[98:99] op_sel_hi:[1,0]
	v_exp_f32_e32 v154, v154
	v_exp_f32_e32 v155, v155
	v_mov_b32_dpp v157, v144 row_ror:2 row_mask:0xf bank_mask:0xf
	v_pk_add_f32 v[154:155], v[154:155], 1.0 op_sel_hi:[1,0]
	v_rcp_f32_e32 v154, v154
	v_rcp_f32_e32 v155, v155
	v_mov_b32_dpp v165, v145 row_ror:2 row_mask:0xf bank_mask:0xf
	v_mov_b32_dpp v156, v144 row_ror:1 row_mask:0xf bank_mask:0xf
	v_mov_b32_dpp v164, v145 row_ror:1 row_mask:0xf bank_mask:0xf
	v_pk_mul_f32 v[150:151], v[150:151], v[154:155]
	v_cndmask_b32_e64 v155, v175, v165, s[6:7]
	v_cndmask_b32_e64 v154, v167, v157, s[6:7]
	v_pk_mul_f32 v[148:149], v[148:149], v[150:151]
	v_cndmask_b32_e64 v151, v164, v168, s[4:5]
	v_cndmask_b32_e64 v150, v156, v166, s[4:5]
	v_pk_mul_f32 v[154:155], v[88:89], v[154:155]
	v_pk_fma_f32 v[150:151], v[92:93], v[150:151], v[154:155]
	v_pk_fma_f32 v[144:145], v[144:145], v[96:97], v[150:151]
	v_pk_mul_f32 v[150:151], v[144:145], s[98:99] op_sel_hi:[1,0]
	v_exp_f32_e32 v150, v150
	v_exp_f32_e32 v151, v151
	v_mov_b32_dpp v155, v146 row_ror:2 row_mask:0xf bank_mask:0xf
	v_pk_add_f32 v[150:151], v[150:151], 1.0 op_sel_hi:[1,0]
	v_rcp_f32_e32 v150, v150
	v_rcp_f32_e32 v151, v151
	v_mov_b32_dpp v167, v147 row_ror:2 row_mask:0xf bank_mask:0xf
	v_mov_b32_dpp v154, v146 row_ror:1 row_mask:0xf bank_mask:0xf
	v_mov_b32_dpp v166, v147 row_ror:1 row_mask:0xf bank_mask:0xf
	v_pk_mul_f32 v[144:145], v[144:145], v[150:151]
	v_cndmask_b32_e64 v151, v170, v167, s[6:7]
	v_cndmask_b32_e64 v150, v163, v155, s[6:7]
	v_pk_mul_f32 v[142:143], v[142:143], v[144:145]
	v_cndmask_b32_e64 v145, v166, v169, s[4:5]
; __device__ __forceinline__ u32x4 pack8(f32x4 a, f32x4 b) { u32x4 w; w.x = cvtpk(a[0], a[1]); w.y = cvtpk(a[2], a[3]); w.z = cvtpk(b[0], b[1]); w.w = cvtpk(b[2], b[3]); return w; }
; __device__ __forceinline__ float dpp_ror1(float v) { return __builtin_bit_cast(float, __builtin_amdgcn_update_dpp(0, __builtin_bit_cast(int, v), 0x121, 0xf, 0xf, false)); }
; __device__ __forceinline__ float dpp_ror2(float v) { return __builtin_bit_cast(float, __builtin_amdgcn_update_dpp(0, __builtin_bit_cast(int, v), 0x122, 0xf, 0xf, false)); }
; __device__ __forceinline__ float silu_mul(float cv, float g) { return cv * __builtin_amdgcn_rcpf(1.f + __builtin_amdgcn_exp2f(-cv * LOG2E)) * g; }
;     __device__ __forceinline__ void operator()(f32x4 (&acc)[2][2][4][2], const Unit& u, int wr, int wc, int fr, int fq) const {
;     ...
;             for (int m = 0; m < 4; ++m) {
;                 const int grow = u.pm * BM + ai * HALF + wr * 64 + m * 16 + fr;
;                 f32x4 av[2];
; #pragma unroll
;                 for (int n = 0; n < 2; ++n)
; #pragma unroll
;                     for (int e = 0; e < 4; ++e) {
;                         const float cur = acc[ai][0][m][n][e], prv = pv[n][e];
;                         const float a1 = dpp_ror1(cur), b1 = dpp_ror1(prv), a2 = dpp_ror2(cur), b2 = dpp_ror2(prv);
;                         const float p1 = fr >= 1 ? a1 : b1, p2 = fr >= 2 ? a2 : b2;
;                         const float cv = w0[n][e] * p2 + w1[n][e] * p1 + w2[n][e] * cur;
;                         av[n][e] = silu_mul(cv, acc[ai][1][m][n][e]);
;                     }
;                 *(u32x4*)(ACT + (size_t)grow * DFF + f0) = pack8(av[0], av[1]);
;                 pv[0] = acc[ai][0][m][0]; pv[1] = acc[ai][0][m][1];
	v_cndmask_b32_e64 v144, v154, v162, s[4:5]
	v_pk_mul_f32 v[150:151], v[90:91], v[150:151]
	v_pk_mul_f32 v[152:153], v[226:227], v[152:153]
	v_pk_fma_f32 v[144:145], v[94:95], v[144:145], v[150:151]
	v_cvt_pk_bf16_f32 v142, v142, v143
	v_pk_fma_f32 v[144:145], v[146:147], v[98:99], v[144:145]
	v_pk_mul_f32 v[146:147], v[144:145], s[98:99] op_sel_hi:[1,0]
	v_exp_f32_e32 v146, v146
	v_exp_f32_e32 v147, v147
	v_mov_b32_dpp v151, v129 row_ror:2 row_mask:0xf bank_mask:0xf
	v_pk_add_f32 v[146:147], v[146:147], 1.0 op_sel_hi:[1,0]
	v_rcp_f32_e32 v146, v146
	v_rcp_f32_e32 v147, v147
	v_mov_b32_dpp v150, v129 row_ror:1 row_mask:0xf bank_mask:0xf
	v_pk_mul_f32 v[144:145], v[144:145], v[146:147]
	s_nop 0
	v_pk_mul_f32 v[144:145], v[140:141], v[144:145]
	v_cvt_pk_bf16_f32 v140, v152, v153
	v_cvt_pk_bf16_f32 v143, v144, v145
	v_mad_i64_i32 v[144:145], s[0:1], v216, s94, v[124:125]
	v_cvt_pk_bf16_f32 v141, v148, v149
	v_lshl_add_u64 v[144:145], v[144:145], 0, v[112:113]
	global_store_dwordx4 v[144:145], v[140:143], off
	v_mov_b32_dpp v145, v138 row_ror:2 row_mask:0xf bank_mask:0xf
	v_mov_b32_dpp v147, v139 row_ror:2 row_mask:0xf bank_mask:0xf
	v_mov_b32_dpp v144, v138 row_ror:1 row_mask:0xf bank_mask:0xf
	v_mov_b32_dpp v146, v139 row_ror:1 row_mask:0xf bank_mask:0xf
	v_cndmask_b32_e64 v143, v161, v147, s[6:7]
	v_cndmask_b32_e64 v142, v159, v145, s[6:7]
	v_cndmask_b32_e64 v141, v146, v160, s[4:5]
	v_cndmask_b32_e64 v140, v144, v158, s[4:5]
	v_pk_mul_f32 v[142:143], v[100:101], v[142:143]
	v_pk_fma_f32 v[140:141], v[104:105], v[140:141], v[142:143]
	v_pk_fma_f32 v[138:139], v[138:139], v[108:109], v[140:141]
	v_pk_mul_f32 v[140:141], v[138:139], s[98:99] op_sel_hi:[1,0]
	v_exp_f32_e32 v140, v140
	v_exp_f32_e32 v141, v141
	v_mov_b32_dpp v143, v134 row_ror:2 row_mask:0xf bank_mask:0xf
	v_pk_add_f32 v[140:141], v[140:141], 1.0 op_sel_hi:[1,0]
	v_rcp_f32_e32 v140, v140
	v_rcp_f32_e32 v141, v141
	v_mov_b32_dpp v149, v135 row_ror:2 row_mask:0xf bank_mask:0xf
	v_mov_b32_dpp v142, v134 row_ror:1 row_mask:0xf bank_mask:0xf
	v_mov_b32_dpp v148, v135 row_ror:1 row_mask:0xf bank_mask:0xf
	v_pk_mul_f32 v[138:139], v[138:139], v[140:141]
	v_cndmask_b32_e64 v141, v203, v149, s[6:7]
	v_cndmask_b32_e64 v140, v172, v143, s[6:7]
	v_pk_mul_f32 v[136:137], v[136:137], v[138:139]
	v_cndmask_b32_e64 v139, v148, v188, s[4:5]
	v_cndmask_b32_e64 v138, v142, v171, s[4:5]
	v_pk_mul_f32 v[140:141], v[102:103], v[140:141]
	v_pk_fma_f32 v[138:139], v[106:107], v[138:139], v[140:141]
	v_pk_fma_f32 v[134:135], v[134:135], v[110:111], v[138:139]
	v_pk_mul_f32 v[138:139], v[134:135], s[98:99] op_sel_hi:[1,0]
	v_exp_f32_e32 v138, v138
	v_exp_f32_e32 v139, v139
	v_mov_b32_dpp v141, v128 row_ror:2 row_mask:0xf bank_mask:0xf
	v_mov_b32_dpp v140, v128 row_ror:1 row_mask:0xf bank_mask:0xf
	v_pk_add_f32 v[138:139], v[138:139], 1.0 op_sel_hi:[1,0]
	v_rcp_f32_e32 v138, v138
	v_rcp_f32_e32 v139, v139
	v_mov_b32_dpp v153, v131 row_ror:2 row_mask:0xf bank_mask:0xf
	v_pk_mul_f32 v[134:135], v[134:135], v[138:139]
	v_cndmask_b32_e64 v139, v165, v151, s[6:7]
	v_cndmask_b32_e64 v138, v157, v141, s[6:7]
	v_pk_mul_f32 v[132:133], v[132:133], v[134:135]
	v_cndmask_b32_e64 v135, v150, v164, s[4:5]
	v_cndmask_b32_e64 v134, v140, v156, s[4:5]
	v_pk_mul_f32 v[138:139], v[88:89], v[138:139]
	v_mov_b32_dpp v152, v131 row_ror:1 row_mask:0xf bank_mask:0xf
	v_pk_fma_f32 v[134:135], v[92:93], v[134:135], v[138:139]
	v_pk_fma_f32 v[128:129], v[128:129], v[96:97], v[134:135]
	v_pk_mul_f32 v[134:135], v[128:129], s[98:99] op_sel_hi:[1,0]
	v_exp_f32_e32 v134, v134
	v_exp_f32_e32 v135, v135
	v_mov_b32_dpp v139, v130 row_ror:2 row_mask:0xf bank_mask:0xf
	v_mov_b32_dpp v138, v130 row_ror:1 row_mask:0xf bank_mask:0xf
	v_pk_add_f32 v[134:135], v[134:135], 1.0 op_sel_hi:[1,0]
	v_rcp_f32_e32 v134, v134
	v_rcp_f32_e32 v135, v135
	s_nop 0
	v_pk_mul_f32 v[128:129], v[128:129], v[134:135]
	v_cndmask_b32_e64 v135, v167, v153, s[6:7]
	v_cndmask_b32_e64 v134, v155, v139, s[6:7]
	v_pk_mul_f32 v[128:129], v[126:127], v[128:129]
	v_cndmask_b32_e64 v127, v152, v166, s[4:5]
	v_cndmask_b32_e64 v126, v138, v154, s[4:5]
	v_pk_mul_f32 v[134:135], v[90:91], v[134:135]
	v_cvt_pk_bf16_f32 v128, v128, v129
	v_pk_fma_f32 v[126:127], v[94:95], v[126:127], v[134:135]
	s_nop 0
	v_pk_fma_f32 v[126:127], v[130:131], v[98:99], v[126:127]
	s_nop 0
	v_pk_mul_f32 v[130:131], v[126:127], s[98:99] op_sel_hi:[1,0]
	v_exp_f32_e32 v130, v130
	v_exp_f32_e32 v131, v131
	s_nop 0
	v_pk_add_f32 v[130:131], v[130:131], 1.0 op_sel_hi:[1,0]
	v_rcp_f32_e32 v130, v130
	v_rcp_f32_e32 v131, v131
	s_nop 0
; __device__ __forceinline__ u32x4 pack8(f32x4 a, f32x4 b) { u32x4 w; w.x = cvtpk(a[0], a[1]); w.y = cvtpk(a[2], a[3]); w.z = cvtpk(b[0], b[1]); w.w = cvtpk(b[2], b[3]); return w; }
; __device__ __forceinline__ float dpp_ror1(float v) { return __builtin_bit_cast(float, __builtin_amdgcn_update_dpp(0, __builtin_bit_cast(int, v), 0x121, 0xf, 0xf, false)); }
; __device__ __forceinline__ float dpp_ror2(float v) { return __builtin_bit_cast(float, __builtin_amdgcn_update_dpp(0, __builtin_bit_cast(int, v), 0x122, 0xf, 0xf, false)); }
; __device__ __forceinline__ float silu_mul(float cv, float g) { return cv * __builtin_amdgcn_rcpf(1.f + __builtin_amdgcn_exp2f(-cv * LOG2E)) * g; }
;     __device__ __forceinline__ void operator()(f32x4 (&acc)[2][2][4][2], const Unit& u, int wr, int wc, int fr, int fq) const {
;     ...
;             for (int m = 0; m < 4; ++m) {
;                 const int grow = u.pm * BM + ai * HALF + wr * 64 + m * 16 + fr;
;                 f32x4 av[2];
; #pragma unroll
;                 for (int n = 0; n < 2; ++n)
; #pragma unroll
;                     for (int e = 0; e < 4; ++e) {
;                         const float cur = acc[ai][0][m][n][e], prv = pv[n][e];
;                         const float a1 = dpp_ror1(cur), b1 = dpp_ror1(prv), a2 = dpp_ror2(cur), b2 = dpp_ror2(prv);
;                         const float p1 = fr >= 1 ? a1 : b1, p2 = fr >= 2 ? a2 : b2;
;                         const float cv = w0[n][e] * p2 + w1[n][e] * p1 + w2[n][e] * cur;
;                         av[n][e] = silu_mul(cv, acc[ai][1][m][n][e]);
;                     }
;                 *(u32x4*)(ACT + (size_t)grow * DFF + f0) = pack8(av[0], av[1]);
;                 pv[0] = acc[ai][0][m][0]; pv[1] = acc[ai][0][m][1];
;             }
	v_pk_mul_f32 v[126:127], v[126:127], v[130:131]
	s_nop 0
	v_pk_mul_f32 v[122:123], v[122:123], v[126:127]
	v_cvt_pk_bf16_f32 v126, v136, v137
	v_cvt_pk_bf16_f32 v129, v122, v123
	v_mad_i64_i32 v[122:123], s[0:1], v212, s94, v[124:125]
	v_cvt_pk_bf16_f32 v127, v132, v133
	v_lshl_add_u64 v[122:123], v[122:123], 0, v[112:113]
	global_store_dwordx4 v[122:123], v[126:129], off
	v_mov_b32_dpp v122, v84 row_ror:1 row_mask:0xf bank_mask:0xf
	s_nop 0
	v_mov_b32_dpp v126, v84 row_ror:2 row_mask:0xf bank_mask:0xf
	v_mov_b32_dpp v127, v85 row_ror:2 row_mask:0xf bank_mask:0xf
	v_mov_b32_dpp v123, v85 row_ror:1 row_mask:0xf bank_mask:0xf
	v_cndmask_b32_e64 v127, v147, v127, s[6:7]
	v_cndmask_b32_e64 v126, v145, v126, s[6:7]
	v_cndmask_b32_e64 v123, v123, v146, s[4:5]
	v_cndmask_b32_e64 v122, v122, v144, s[4:5]
	v_pk_mul_f32 v[126:127], v[100:101], v[126:127]
	s_nop 0
	v_pk_fma_f32 v[122:123], v[104:105], v[122:123], v[126:127]
	s_nop 0
	v_pk_fma_f32 v[84:85], v[84:85], v[108:109], v[122:123]
	s_nop 0
	v_pk_mul_f32 v[122:123], v[84:85], s[98:99] op_sel_hi:[1,0]
	v_exp_f32_e32 v122, v122
	v_exp_f32_e32 v123, v123
	s_nop 0
	v_pk_add_f32 v[122:123], v[122:123], 1.0 op_sel_hi:[1,0]
	v_rcp_f32_e32 v122, v122
	v_rcp_f32_e32 v123, v123
	s_nop 0
	v_pk_mul_f32 v[84:85], v[84:85], v[122:123]
	v_pk_mul_f32 v[84:85], v[120:121], v[84:85]
	v_mov_b32_dpp v122, v86 row_ror:2 row_mask:0xf bank_mask:0xf
	v_mov_b32_dpp v123, v87 row_ror:2 row_mask:0xf bank_mask:0xf
	v_mov_b32_dpp v120, v86 row_ror:1 row_mask:0xf bank_mask:0xf
	v_mov_b32_dpp v121, v87 row_ror:1 row_mask:0xf bank_mask:0xf
	v_cndmask_b32_e64 v123, v149, v123, s[6:7]
	v_cndmask_b32_e64 v122, v143, v122, s[6:7]
	v_cndmask_b32_e64 v121, v121, v148, s[4:5]
	v_cndmask_b32_e64 v120, v120, v142, s[4:5]
	v_pk_mul_f32 v[122:123], v[102:103], v[122:123]
	s_nop 0
	v_pk_fma_f32 v[120:121], v[106:107], v[120:121], v[122:123]
	s_nop 0
	v_pk_fma_f32 v[86:87], v[86:87], v[110:111], v[120:121]
	s_nop 0
	v_pk_mul_f32 v[120:121], v[86:87], s[98:99] op_sel_hi:[1,0]
	v_exp_f32_e32 v120, v120
	v_exp_f32_e32 v121, v121
	s_nop 0
	v_pk_add_f32 v[120:121], v[120:121], 1.0 op_sel_hi:[1,0]
	v_rcp_f32_e32 v120, v120
	v_rcp_f32_e32 v121, v121
	s_nop 0
	v_pk_mul_f32 v[86:87], v[86:87], v[120:121]
	v_pk_mul_f32 v[86:87], v[118:119], v[86:87]
	v_mov_b32_dpp v120, v80 row_ror:2 row_mask:0xf bank_mask:0xf
	v_mov_b32_dpp v121, v81 row_ror:2 row_mask:0xf bank_mask:0xf
	v_mov_b32_dpp v118, v80 row_ror:1 row_mask:0xf bank_mask:0xf
	v_mov_b32_dpp v119, v81 row_ror:1 row_mask:0xf bank_mask:0xf
	v_cndmask_b32_e64 v121, v151, v121, s[6:7]
	v_cndmask_b32_e64 v120, v141, v120, s[6:7]
	v_cndmask_b32_e64 v119, v119, v150, s[4:5]
	v_cndmask_b32_e64 v118, v118, v140, s[4:5]
	v_pk_mul_f32 v[120:121], v[88:89], v[120:121]
	s_nop 0
	v_pk_fma_f32 v[118:119], v[92:93], v[118:119], v[120:121]
	s_nop 0
	v_pk_fma_f32 v[80:81], v[80:81], v[96:97], v[118:119]
	s_nop 0
	v_pk_mul_f32 v[118:119], v[80:81], s[98:99] op_sel_hi:[1,0]
	v_exp_f32_e32 v118, v118
	v_exp_f32_e32 v119, v119
	s_nop 0
	v_pk_add_f32 v[118:119], v[118:119], 1.0 op_sel_hi:[1,0]
	v_rcp_f32_e32 v118, v118
	v_rcp_f32_e32 v119, v119
	s_nop 0
	v_pk_mul_f32 v[80:81], v[80:81], v[118:119]
	v_pk_mul_f32 v[116:117], v[116:117], v[80:81]
	v_mov_b32_dpp v118, v82 row_ror:2 row_mask:0xf bank_mask:0xf
	v_mov_b32_dpp v119, v83 row_ror:2 row_mask:0xf bank_mask:0xf
	v_mov_b32_dpp v80, v82 row_ror:1 row_mask:0xf bank_mask:0xf
	v_mov_b32_dpp v81, v83 row_ror:1 row_mask:0xf bank_mask:0xf
	v_cndmask_b32_e64 v119, v153, v119, s[6:7]
	v_cndmask_b32_e64 v118, v139, v118, s[6:7]
	v_cndmask_b32_e64 v81, v81, v152, s[4:5]
	v_cndmask_b32_e64 v80, v80, v138, s[4:5]
	v_pk_mul_f32 v[118:119], v[90:91], v[118:119]
	s_nop 0
	v_pk_fma_f32 v[80:81], v[94:95], v[80:81], v[118:119]
	s_nop 0
	v_pk_fma_f32 v[80:81], v[82:83], v[98:99], v[80:81]
	s_nop 0
	v_pk_mul_f32 v[82:83], v[80:81], s[98:99] op_sel_hi:[1,0]
	v_exp_f32_e32 v82, v82
	v_exp_f32_e32 v83, v83
	s_nop 0
	v_pk_add_f32 v[82:83], v[82:83], 1.0 op_sel_hi:[1,0]
	v_rcp_f32_e32 v82, v82
	v_rcp_f32_e32 v83, v83
	s_nop 0
	v_pk_mul_f32 v[80:81], v[80:81], v[82:83]
	s_nop 0
	v_pk_mul_f32 v[114:115], v[114:115], v[80:81]
	v_cvt_pk_bf16_f32 v80, v84, v85
	v_mad_i64_i32 v[84:85], s[0:1], v210, s94, v[124:125]
	v_cvt_pk_bf16_f32 v81, v86, v87
	v_cvt_pk_bf16_f32 v82, v116, v117
	v_cvt_pk_bf16_f32 v83, v114, v115
	v_lshl_add_u64 v[84:85], v[84:85], 0, v[112:113]
	s_mov_b64 s[0:1], -1
	global_store_dwordx4 v[84:85], v[80:83], off
	s_cbranch_vccnz .LBB0_1189
	ds_read_b128 v[84:87], v230
	ds_read_b128 v[80:83], v230 offset:16
	s_mov_b64 s[0:1], 0

; __device__ __forceinline__ u32x4 pack8(f32x4 a, f32x4 b) { u32x4 w; w.x = cvtpk(a[0], a[1]); w.y = cvtpk(a[2], a[3]); w.z = cvtpk(b[0], b[1]); w.w = cvtpk(b[2], b[3]); return w; }
; #define FOR_AI_M _Pragma("unroll") for (int ai = 0; ai < 2; ++ai) _Pragma("unroll") for (int m = 0; m < 4; ++m)
; #define FOR_BJ _Pragma("unroll") for (int bj = 0; bj < 2; ++bj)
; __device__ __forceinline__ float dpp_ror1(float v) { return __builtin_bit_cast(float, __builtin_amdgcn_update_dpp(0, __builtin_bit_cast(int, v), 0x121, 0xf, 0xf, false)); }
; __device__ __forceinline__ float dpp_ror2(float v) { return __builtin_bit_cast(float, __builtin_amdgcn_update_dpp(0, __builtin_bit_cast(int, v), 0x122, 0xf, 0xf, false)); }
; __device__ __forceinline__ float silu_mul(float cv, float g) { return cv * __builtin_amdgcn_rcpf(1.f + __builtin_amdgcn_exp2f(-cv * LOG2E)) * g; }
;     __device__ __forceinline__ void operator()(f32x4 (&acc)[2][2][4][2], const Unit& u, int wr, int wc, int fr, int fq) const {
;     ...
;         FOR_AI_M { const int grow = u.pm * BM + ai * HALF + wr * 64 + m * 16 + fr;
;             const f32x4 a0 = *(const f32x4*)(SS3 + (size_t)grow * 8), a1 = *(const f32x4*)(SS3 + (size_t)grow * 8 + 4);
;             const float r3 = rsqrtf(((a0[0] + a0[1]) + (a0[2] + a0[3]) + (a1[0] + a1[1]) + (a1[2] + a1[3])) * (1.f / 2048.f) + EPS);
;             FOR_BJ { acc[ai][bj][m][0] *= r3; acc[ai][bj][m][1] *= r3; } }
;     ...
;             for (int m = 0; m < 4; ++m) {
;                 const int grow = u.pm * BM + ai * HALF + wr * 64 + m * 16 + fr;
;                 f32x4 av[2];
; #pragma unroll
;                 for (int n = 0; n < 2; ++n)
; #pragma unroll
;                     for (int e = 0; e < 4; ++e) {
;                         const float cur = acc[ai][0][m][n][e], prv = pv[n][e];
;                         const float a1 = dpp_ror1(cur), b1 = dpp_ror1(prv), a2 = dpp_ror2(cur), b2 = dpp_ror2(prv);
;                         const float p1 = fr >= 1 ? a1 : b1, p2 = fr >= 2 ? a2 : b2;
;                         const float cv = w0[n][e] * p2 + w1[n][e] * p1 + w2[n][e] * cur;
;                         av[n][e] = silu_mul(cv, acc[ai][1][m][n][e]);
;                     }
;                 *(u32x4*)(ACT + (size_t)grow * DFF + f0) = pack8(av[0], av[1]);
;                 pv[0] = acc[ai][0][m][0]; pv[1] = acc[ai][0][m][1];
.LBB0_1191:
	v_mov_b32_e32 v114, v77
	v_mov_b32_e32 v115, v78
	v_mov_b32_e32 v77, v79
	v_mov_b32_e32 v78, v74
	v_mov_b32_e32 v79, v72
	v_mov_b32_e32 v72, v75
	v_mov_b32_e32 v74, v69
	v_mov_b32_e32 v75, v70
	v_mov_b32_e32 v69, v71
	v_pk_add_f32 v[76:77], v[114:115], v[76:77]
	v_pk_add_f32 v[68:69], v[74:75], v[68:69]
	v_mov_b32_e32 v70, v66
	v_mov_b32_e32 v71, v64
	v_mov_b32_e32 v64, v67
	v_pk_add_f32 v[72:73], v[78:79], v[72:73]
	v_pk_add_f32 v[64:65], v[70:71], v[64:65]
	v_mov_b32_e32 v66, v68
	v_mov_b32_e32 v67, v76
	v_mov_b32_e32 v76, v69
	v_pk_add_f32 v[66:67], v[66:67], v[76:77]
	v_mov_b32_e32 v68, v65
	v_mov_b32_e32 v69, v73
	v_pk_add_f32 v[66:67], v[66:67], v[68:69]
	v_mov_b32_e32 v65, v72
	v_pk_add_f32 v[64:65], v[64:65], v[66:67]
	v_pk_fma_f32 v[64:65], v[64:65], s[58:59], v[200:201] op_sel_hi:[1,0,0]
	v_mov_b32_e32 v74, 0
	v_mul_f32_e32 v66, 0x4b800000, v65
	v_cmp_gt_f32_e32 vcc, s85, v65
	v_mov_b32_e32 v77, 0
	v_mov_b32_e32 v79, 0
	v_cndmask_b32_e32 v65, v65, v66, vcc
	v_rsq_f32_e32 v65, v65
	v_mov_b32_e32 v76, 0
	v_mov_b32_e32 v78, 0
	v_mov_b32_e32 v215, v214
	v_mul_f32_e32 v66, 0x45800000, v65
	v_cndmask_b32_e32 v66, v65, v66, vcc
	v_pk_mul_f32 v[68:69], v[38:39], v[66:67] op_sel_hi:[1,0]
	v_mul_f32_e32 v38, 0x4b800000, v64
	v_cmp_gt_f32_e32 vcc, s85, v64
	v_pk_mul_f32 v[54:55], v[54:55], v[66:67] op_sel_hi:[1,0]
	v_pk_mul_f32 v[52:53], v[52:53], v[66:67] op_sel_hi:[1,0]
	v_cndmask_b32_e32 v38, v64, v38, vcc
	v_rsq_f32_e32 v38, v38
	v_pk_mul_f32 v[50:51], v[50:51], v[66:67] op_sel_hi:[1,0]
	v_pk_mul_f32 v[48:49], v[48:49], v[66:67] op_sel_hi:[1,0]
	v_pk_mul_f32 v[64:65], v[36:37], v[66:67] op_sel_hi:[1,0]
	v_pk_mul_f32 v[70:71], v[34:35], v[66:67] op_sel_hi:[1,0]
	v_pk_mul_f32 v[66:67], v[32:33], v[66:67] op_sel_hi:[1,0]
	v_mul_f32_e32 v32, 0x45800000, v38
	v_cndmask_b32_e32 v38, v38, v32, vcc
	v_pk_mul_f32 v[32:33], v[22:23], v[38:39] op_sel_hi:[1,0]
	v_mul_f32_e32 v22, 0x4b800000, v219
	v_cndmask_b32_e64 v22, v219, v22, s[8:9]
	v_rsq_f32_e32 v22, v22
	v_pk_mul_f32 v[46:47], v[46:47], v[38:39] op_sel_hi:[1,0]
	v_pk_mul_f32 v[44:45], v[44:45], v[38:39] op_sel_hi:[1,0]
	v_pk_mul_f32 v[36:37], v[42:43], v[38:39] op_sel_hi:[1,0]
	v_pk_mul_f32 v[40:41], v[40:41], v[38:39] op_sel_hi:[1,0]
	v_pk_mul_f32 v[42:43], v[20:21], v[38:39] op_sel_hi:[1,0]
	v_pk_mul_f32 v[34:35], v[18:19], v[38:39] op_sel_hi:[1,0]
	v_pk_mul_f32 v[38:39], v[16:17], v[38:39] op_sel_hi:[1,0]
	v_mul_f32_e32 v16, 0x45800000, v22
	v_cndmask_b32_e64 v72, v22, v16, s[8:9]
	v_pk_mul_f32 v[20:21], v[30:31], v[72:73] op_sel_hi:[1,0]
	v_pk_mul_f32 v[28:29], v[28:29], v[72:73] op_sel_hi:[1,0]
	v_pk_mul_f32 v[16:17], v[26:27], v[72:73] op_sel_hi:[1,0]
	v_pk_mul_f32 v[18:19], v[24:25], v[72:73] op_sel_hi:[1,0]
	v_pk_mul_f32 v[14:15], v[14:15], v[72:73] op_sel_hi:[1,0]
	v_pk_mul_f32 v[22:23], v[12:13], v[72:73] op_sel_hi:[1,0]
	v_pk_mul_f32 v[10:11], v[10:11], v[72:73] op_sel_hi:[1,0]
	v_pk_mul_f32 v[8:9], v[8:9], v[72:73] op_sel_hi:[1,0]
	v_mov_b32_dpp v73, v52 row_ror:2 row_mask:0xf bank_mask:0xf
	s_waitcnt vmcnt(0) lgkmcnt(1)
	v_mov_b32_dpp v26, v84 row_ror:2 row_mask:0xf bank_mask:0xf
	v_mov_b32_dpp v75, v53 row_ror:2 row_mask:0xf bank_mask:0xf
	v_mov_b32_dpp v27, v85 row_ror:2 row_mask:0xf bank_mask:0xf
	v_mov_b32_dpp v72, v52 row_ror:1 row_mask:0xf bank_mask:0xf
	v_mov_b32_dpp v24, v84 row_ror:1 row_mask:0xf bank_mask:0xf
	v_mov_b32_dpp v74, v53 row_ror:1 row_mask:0xf bank_mask:0xf
	v_mov_b32_dpp v25, v85 row_ror:1 row_mask:0xf bank_mask:0xf
	v_cndmask_b32_e64 v27, v27, v75, s[6:7]
	v_cndmask_b32_e64 v26, v26, v73, s[6:7]
	v_cndmask_b32_e64 v25, v74, v25, s[4:5]
	v_cndmask_b32_e64 v24, v72, v24, s[4:5]
	v_pk_mul_f32 v[26:27], v[100:101], v[26:27]
	v_mov_b32_e32 v12, v214
	v_pk_fma_f32 v[24:25], v[104:105], v[24:25], v[26:27]
	v_mov_b32_e32 v13, v214
	v_pk_fma_f32 v[24:25], v[52:53], v[108:109], v[24:25]
	v_pk_mul_f32 v[6:7], v[6:7], v[12:13]
	v_pk_mul_f32 v[26:27], v[24:25], s[98:99] op_sel_hi:[1,0]
	v_exp_f32_e32 v26, v26
	v_exp_f32_e32 v27, v27
	v_pk_mul_f32 v[2:3], v[2:3], v[12:13]
	v_mov_b32_dpp v77, v54 row_ror:2 row_mask:0xf bank_mask:0xf
	v_pk_add_f32 v[26:27], v[26:27], 1.0 op_sel_hi:[1,0]
	v_rcp_f32_e32 v26, v26
	v_rcp_f32_e32 v27, v27
	v_mov_b32_dpp v79, v55 row_ror:2 row_mask:0xf bank_mask:0xf
	v_mov_b32_dpp v76, v54 row_ror:1 row_mask:0xf bank_mask:0xf
	v_mov_b32_dpp v78, v55 row_ror:1 row_mask:0xf bank_mask:0xf
	v_pk_mul_f32 v[12:13], v[24:25], v[26:27]
	v_mov_b32_dpp v26, v86 row_ror:2 row_mask:0xf bank_mask:0xf
	v_mov_b32_dpp v27, v87 row_ror:2 row_mask:0xf bank_mask:0xf
	v_mov_b32_dpp v24, v86 row_ror:1 row_mask:0xf bank_mask:0xf
	v_mov_b32_dpp v25, v87 row_ror:1 row_mask:0xf bank_mask:0xf
	v_cndmask_b32_e64 v27, v27, v79, s[6:7]
	v_cndmask_b32_e64 v26, v26, v77, s[6:7]
	v_cndmask_b32_e64 v25, v78, v25, s[4:5]
	v_cndmask_b32_e64 v24, v76, v24, s[4:5]
	v_pk_mul_f32 v[26:27], v[102:103], v[26:27]
	v_pk_mul_f32 v[12:13], v[64:65], v[12:13]
	v_pk_fma_f32 v[24:25], v[106:107], v[24:25], v[26:27]
	v_pk_fma_f32 v[24:25], v[54:55], v[110:111], v[24:25]
	v_pk_mul_f32 v[26:27], v[24:25], s[98:99] op_sel_hi:[1,0]
	v_mov_b32_dpp v55, v48 row_ror:2 row_mask:0xf bank_mask:0xf
	s_waitcnt lgkmcnt(0)
; __device__ __forceinline__ u32x4 pack8(f32x4 a, f32x4 b) { u32x4 w; w.x = cvtpk(a[0], a[1]); w.y = cvtpk(a[2], a[3]); w.z = cvtpk(b[0], b[1]); w.w = cvtpk(b[2], b[3]); return w; }
; __device__ __forceinline__ float dpp_ror1(float v) { return __builtin_bit_cast(float, __builtin_amdgcn_update_dpp(0, __builtin_bit_cast(int, v), 0x121, 0xf, 0xf, false)); }
; __device__ __forceinline__ float dpp_ror2(float v) { return __builtin_bit_cast(float, __builtin_amdgcn_update_dpp(0, __builtin_bit_cast(int, v), 0x122, 0xf, 0xf, false)); }
; __device__ __forceinline__ float silu_mul(float cv, float g) { return cv * __builtin_amdgcn_rcpf(1.f + __builtin_amdgcn_exp2f(-cv * LOG2E)) * g; }
;     __device__ __forceinline__ void operator()(f32x4 (&acc)[2][2][4][2], const Unit& u, int wr, int wc, int fr, int fq) const {
;     ...
;             for (int m = 0; m < 4; ++m) {
;                 const int grow = u.pm * BM + ai * HALF + wr * 64 + m * 16 + fr;
;                 f32x4 av[2];
; #pragma unroll
;                 for (int n = 0; n < 2; ++n)
; #pragma unroll
;                     for (int e = 0; e < 4; ++e) {
;                         const float cur = acc[ai][0][m][n][e], prv = pv[n][e];
;                         const float a1 = dpp_ror1(cur), b1 = dpp_ror1(prv), a2 = dpp_ror2(cur), b2 = dpp_ror2(prv);
;                         const float p1 = fr >= 1 ? a1 : b1, p2 = fr >= 2 ? a2 : b2;
;                         const float cv = w0[n][e] * p2 + w1[n][e] * p1 + w2[n][e] * cur;
;                         av[n][e] = silu_mul(cv, acc[ai][1][m][n][e]);
;                     }
;                 *(u32x4*)(ACT + (size_t)grow * DFF + f0) = pack8(av[0], av[1]);
;                 pv[0] = acc[ai][0][m][0]; pv[1] = acc[ai][0][m][1];
	v_mov_b32_dpp v52, v80 row_ror:2 row_mask:0xf bank_mask:0xf
	v_mov_b32_dpp v65, v49 row_ror:2 row_mask:0xf bank_mask:0xf
	v_mov_b32_dpp v53, v81 row_ror:2 row_mask:0xf bank_mask:0xf
	v_exp_f32_e32 v26, v26
	v_exp_f32_e32 v27, v27
	v_mov_b32_dpp v54, v48 row_ror:1 row_mask:0xf bank_mask:0xf
	v_mov_b32_dpp v30, v80 row_ror:1 row_mask:0xf bank_mask:0xf
	v_mov_b32_dpp v64, v49 row_ror:1 row_mask:0xf bank_mask:0xf
	v_mov_b32_dpp v31, v81 row_ror:1 row_mask:0xf bank_mask:0xf
	v_cndmask_b32_e64 v53, v53, v65, s[6:7]
	v_cndmask_b32_e64 v52, v52, v55, s[6:7]
	v_cndmask_b32_e64 v31, v64, v31, s[4:5]
	v_cndmask_b32_e64 v30, v54, v30, s[4:5]
	v_pk_mul_f32 v[52:53], v[88:89], v[52:53]
	v_pk_fma_f32 v[30:31], v[92:93], v[30:31], v[52:53]
	v_pk_add_f32 v[26:27], v[26:27], 1.0 op_sel_hi:[1,0]
	v_pk_fma_f32 v[30:31], v[48:49], v[96:97], v[30:31]
	v_rcp_f32_e32 v26, v26
	v_mul_f32_e32 v48, 0xbfb8aa3b, v30
	v_rcp_f32_e32 v27, v27
	v_exp_f32_e32 v48, v48
	v_mul_f32_e32 v49, 0xbfb8aa3b, v31
	v_exp_f32_e32 v49, v49
	v_pk_mul_f32 v[24:25], v[24:25], v[26:27]
	v_add_f32_e32 v26, 1.0, v48
	v_add_f32_e32 v27, 1.0, v49
	v_mov_b32_dpp v48, v82 row_ror:1 row_mask:0xf bank_mask:0xf
	v_mov_b32_dpp v81, v50 row_ror:2 row_mask:0xf bank_mask:0xf
	v_mov_b32_dpp v52, v82 row_ror:2 row_mask:0xf bank_mask:0xf
	v_mov_b32_dpp v84, v51 row_ror:2 row_mask:0xf bank_mask:0xf
	v_mov_b32_dpp v53, v83 row_ror:2 row_mask:0xf bank_mask:0xf
	v_mov_b32_dpp v80, v50 row_ror:1 row_mask:0xf bank_mask:0xf
	v_mov_b32_dpp v82, v51 row_ror:1 row_mask:0xf bank_mask:0xf
	v_mov_b32_dpp v49, v83 row_ror:1 row_mask:0xf bank_mask:0xf
	v_cndmask_b32_e64 v53, v53, v84, s[6:7]
	v_cndmask_b32_e64 v52, v52, v81, s[6:7]
	v_cndmask_b32_e64 v49, v82, v49, s[4:5]
	v_cndmask_b32_e64 v48, v80, v48, s[4:5]
	v_pk_mul_f32 v[52:53], v[90:91], v[52:53]
	v_rcp_f32_e32 v26, v26
	v_pk_fma_f32 v[48:49], v[94:95], v[48:49], v[52:53]
	v_rcp_f32_e32 v27, v27
	v_pk_fma_f32 v[48:49], v[50:51], v[98:99], v[48:49]
	v_pk_mul_f32 v[52:53], v[68:69], v[24:25]
	v_pk_mul_f32 v[50:51], v[48:49], s[98:99] op_sel_hi:[1,0]
	v_exp_f32_e32 v50, v50
	v_exp_f32_e32 v51, v51
	v_pk_mul_f32 v[24:25], v[30:31], v[26:27]
	v_pk_add_f32 v[50:51], v[50:51], 1.0 op_sel_hi:[1,0]
	v_rcp_f32_e32 v50, v50
	v_rcp_f32_e32 v51, v51
	v_pk_mul_f32 v[26:27], v[66:67], v[24:25]
	v_cvt_pk_bf16_f32 v26, v26, v27
	v_pk_mul_f32 v[24:25], v[48:49], v[50:51]
	v_pk_mul_f32 v[30:31], v[70:71], v[24:25]
	v_cvt_pk_bf16_f32 v25, v52, v53
	v_mov_b32_dpp v51, v44 row_ror:2 row_mask:0xf bank_mask:0xf
	v_mov_b32_dpp v53, v45 row_ror:2 row_mask:0xf bank_mask:0xf
	v_cvt_pk_bf16_f32 v27, v30, v31
	v_mov_b32_dpp v50, v44 row_ror:1 row_mask:0xf bank_mask:0xf
	v_mov_b32_dpp v52, v45 row_ror:1 row_mask:0xf bank_mask:0xf
	v_cndmask_b32_e64 v31, v75, v53, s[6:7]
	v_cndmask_b32_e64 v30, v73, v51, s[6:7]
	v_cvt_pk_bf16_f32 v24, v12, v13
	v_cndmask_b32_e64 v13, v52, v74, s[4:5]
	v_cndmask_b32_e64 v12, v50, v72, s[4:5]
	v_pk_mul_f32 v[30:31], v[100:101], v[30:31]
	v_pk_fma_f32 v[12:13], v[104:105], v[12:13], v[30:31]
	v_mov_b32_dpp v67, v47 row_ror:2 row_mask:0xf bank_mask:0xf
	v_pk_fma_f32 v[30:31], v[44:45], v[108:109], v[12:13]
	v_mov_b32_dpp v66, v47 row_ror:1 row_mask:0xf bank_mask:0xf
	v_mul_f32_e32 v12, 0xbfb8aa3b, v30
	v_exp_f32_e32 v44, v12
	v_mul_f32_e32 v12, 0xbfb8aa3b, v31
	v_exp_f32_e32 v45, v12
	v_mov_b64_e32 v[12:13], s[14:15]
	v_add_f32_e32 v44, 1.0, v44
	v_rcp_f32_e32 v44, v44
	v_add_f32_e32 v45, 1.0, v45
	v_rcp_f32_e32 v45, v45
	v_mad_i64_i32 v[48:49], s[0:1], v208, s94, v[12:13]
	v_lshl_add_u64 v[48:49], v[48:49], 0, v[112:113]
	global_store_dwordx4 v[48:49], v[24:27], off
	s_nop 1
	v_pk_mul_f32 v[24:25], v[30:31], v[44:45]
	v_mov_b32_dpp v49, v46 row_ror:2 row_mask:0xf bank_mask:0xf
	v_mov_b32_dpp v48, v46 row_ror:1 row_mask:0xf bank_mask:0xf
	v_cndmask_b32_e64 v31, v79, v67, s[6:7]
	v_cndmask_b32_e64 v30, v77, v49, s[6:7]
	v_cndmask_b32_e64 v27, v66, v78, s[4:5]
	v_cndmask_b32_e64 v26, v48, v76, s[4:5]
	v_pk_mul_f32 v[30:31], v[102:103], v[30:31]
	v_pk_fma_f32 v[26:27], v[106:107], v[26:27], v[30:31]
	v_mov_b32_dpp v69, v41 row_ror:2 row_mask:0xf bank_mask:0xf
	v_pk_fma_f32 v[26:27], v[46:47], v[110:111], v[26:27]
	v_pk_mul_f32 v[30:31], v[26:27], s[98:99] op_sel_hi:[1,0]
	v_mov_b32_dpp v47, v40 row_ror:2 row_mask:0xf bank_mask:0xf
	v_exp_f32_e32 v30, v30
	v_exp_f32_e32 v31, v31
	v_mov_b32_dpp v46, v40 row_ror:1 row_mask:0xf bank_mask:0xf
	v_mov_b32_dpp v68, v41 row_ror:1 row_mask:0xf bank_mask:0xf
	v_cndmask_b32_e64 v45, v65, v69, s[6:7]
	v_cndmask_b32_e64 v44, v55, v47, s[6:7]
	v_pk_mul_f32 v[24:25], v[42:43], v[24:25]
	v_cndmask_b32_e64 v43, v68, v64, s[4:5]
	v_cndmask_b32_e64 v42, v46, v54, s[4:5]
	v_pk_mul_f32 v[44:45], v[88:89], v[44:45]
	v_pk_fma_f32 v[42:43], v[92:93], v[42:43], v[44:45]
	v_pk_add_f32 v[30:31], v[30:31], 1.0 op_sel_hi:[1,0]
	v_pk_fma_f32 v[40:41], v[40:41], v[96:97], v[42:43]
	v_rcp_f32_e32 v30, v30
	v_pk_mul_f32 v[42:43], v[40:41], s[98:99] op_sel_hi:[1,0]
	v_rcp_f32_e32 v31, v31
	v_exp_f32_e32 v42, v42
	v_exp_f32_e32 v43, v43
	v_mov_b32_dpp v55, v36 row_ror:2 row_mask:0xf bank_mask:0xf
	v_mov_b32_dpp v65, v37 row_ror:2 row_mask:0xf bank_mask:0xf
	v_mov_b32_dpp v54, v36 row_ror:1 row_mask:0xf bank_mask:0xf
	v_mov_b32_dpp v64, v37 row_ror:1 row_mask:0xf bank_mask:0xf
	v_cndmask_b32_e64 v45, v84, v65, s[6:7]
	v_cndmask_b32_e64 v44, v81, v55, s[6:7]
	v_pk_mul_f32 v[26:27], v[26:27], v[30:31]
	v_add_f32_e32 v30, 1.0, v42
	v_add_f32_e32 v31, 1.0, v43
	v_cndmask_b32_e64 v43, v64, v82, s[4:5]
	v_cndmask_b32_e64 v42, v54, v80, s[4:5]
	v_pk_mul_f32 v[44:45], v[90:91], v[44:45]
	v_rcp_f32_e32 v30, v30
	v_pk_fma_f32 v[42:43], v[94:95], v[42:43], v[44:45]
; __device__ __forceinline__ u32x4 pack8(f32x4 a, f32x4 b) { u32x4 w; w.x = cvtpk(a[0], a[1]); w.y = cvtpk(a[2], a[3]); w.z = cvtpk(b[0], b[1]); w.w = cvtpk(b[2], b[3]); return w; }
; __device__ __forceinline__ float dpp_ror1(float v) { return __builtin_bit_cast(float, __builtin_amdgcn_update_dpp(0, __builtin_bit_cast(int, v), 0x121, 0xf, 0xf, false)); }
; __device__ __forceinline__ float dpp_ror2(float v) { return __builtin_bit_cast(float, __builtin_amdgcn_update_dpp(0, __builtin_bit_cast(int, v), 0x122, 0xf, 0xf, false)); }
; __device__ __forceinline__ float silu_mul(float cv, float g) { return cv * __builtin_amdgcn_rcpf(1.f + __builtin_amdgcn_exp2f(-cv * LOG2E)) * g; }
;     __device__ __forceinline__ void operator()(f32x4 (&acc)[2][2][4][2], const Unit& u, int wr, int wc, int fr, int fq) const {
;     ...
;             for (int m = 0; m < 4; ++m) {
;                 const int grow = u.pm * BM + ai * HALF + wr * 64 + m * 16 + fr;
;                 f32x4 av[2];
; #pragma unroll
;                 for (int n = 0; n < 2; ++n)
; #pragma unroll
;                     for (int e = 0; e < 4; ++e) {
;                         const float cur = acc[ai][0][m][n][e], prv = pv[n][e];
;                         const float a1 = dpp_ror1(cur), b1 = dpp_ror1(prv), a2 = dpp_ror2(cur), b2 = dpp_ror2(prv);
;                         const float p1 = fr >= 1 ? a1 : b1, p2 = fr >= 2 ? a2 : b2;
;                         const float cv = w0[n][e] * p2 + w1[n][e] * p1 + w2[n][e] * cur;
;                         av[n][e] = silu_mul(cv, acc[ai][1][m][n][e]);
;                     }
;                 *(u32x4*)(ACT + (size_t)grow * DFF + f0) = pack8(av[0], av[1]);
;                 pv[0] = acc[ai][0][m][0]; pv[1] = acc[ai][0][m][1];
	v_rcp_f32_e32 v31, v31
	v_pk_fma_f32 v[36:37], v[36:37], v[98:99], v[42:43]
	v_pk_mul_f32 v[26:27], v[32:33], v[26:27]
	v_pk_mul_f32 v[42:43], v[36:37], s[98:99] op_sel_hi:[1,0]
	v_exp_f32_e32 v42, v42
	v_exp_f32_e32 v43, v43
	v_pk_mul_f32 v[30:31], v[40:41], v[30:31]
	v_cvt_pk_bf16_f32 v24, v24, v25
	v_pk_add_f32 v[42:43], v[42:43], 1.0 op_sel_hi:[1,0]
	v_rcp_f32_e32 v42, v42
	v_rcp_f32_e32 v43, v43
	v_pk_mul_f32 v[30:31], v[38:39], v[30:31]
	v_pk_mul_f32 v[32:33], v[36:37], v[42:43]
	v_mov_b32_dpp v39, v29 row_ror:2 row_mask:0xf bank_mask:0xf
	v_mov_b32_dpp v37, v28 row_ror:2 row_mask:0xf bank_mask:0xf
	v_pk_mul_f32 v[32:33], v[34:35], v[32:33]
	v_mov_b32_dpp v36, v28 row_ror:1 row_mask:0xf bank_mask:0xf
	v_mov_b32_dpp v38, v29 row_ror:1 row_mask:0xf bank_mask:0xf
	v_cndmask_b32_e64 v35, v53, v39, s[6:7]
	v_cndmask_b32_e64 v34, v51, v37, s[6:7]
	v_cvt_pk_bf16_f32 v25, v26, v27
	v_cvt_pk_bf16_f32 v26, v30, v31
	v_cndmask_b32_e64 v31, v38, v52, s[4:5]
	v_cndmask_b32_e64 v30, v36, v50, s[4:5]
	v_pk_mul_f32 v[34:35], v[100:101], v[34:35]
	v_pk_fma_f32 v[30:31], v[104:105], v[30:31], v[34:35]
	v_pk_fma_f32 v[28:29], v[28:29], v[108:109], v[30:31]
	v_mul_f32_e32 v27, 0xbfb8aa3b, v28
	v_exp_f32_e32 v30, v27
	v_mul_f32_e32 v27, 0xbfb8aa3b, v29
	v_exp_f32_e32 v31, v27
	v_cvt_pk_bf16_f32 v27, v32, v33
	v_add_f32_e32 v30, 1.0, v30
	v_rcp_f32_e32 v30, v30
	v_add_f32_e32 v31, 1.0, v31
	v_rcp_f32_e32 v31, v31
	v_mad_i64_i32 v[32:33], s[0:1], v204, s94, v[12:13]
	v_lshl_add_u64 v[32:33], v[32:33], 0, v[112:113]
	global_store_dwordx4 v[32:33], v[24:27], off
	s_nop 1
	v_pk_mul_f32 v[24:25], v[28:29], v[30:31]
	v_mov_b32_dpp v33, v21 row_ror:2 row_mask:0xf bank_mask:0xf
	v_mov_b32_dpp v31, v20 row_ror:2 row_mask:0xf bank_mask:0xf
	v_mov_b32_dpp v30, v20 row_ror:1 row_mask:0xf bank_mask:0xf
	v_mov_b32_dpp v32, v21 row_ror:1 row_mask:0xf bank_mask:0xf
	v_cndmask_b32_e64 v29, v67, v33, s[6:7]
	v_cndmask_b32_e64 v28, v49, v31, s[6:7]
	v_cndmask_b32_e64 v27, v32, v66, s[4:5]
	v_cndmask_b32_e64 v26, v30, v48, s[4:5]
	v_pk_mul_f32 v[28:29], v[102:103], v[28:29]
	v_mov_b32_dpp v35, v18 row_ror:2 row_mask:0xf bank_mask:0xf
	v_pk_fma_f32 v[26:27], v[106:107], v[26:27], v[28:29]
	v_pk_fma_f32 v[20:21], v[20:21], v[110:111], v[26:27]
	v_mov_b32_dpp v41, v19 row_ror:2 row_mask:0xf bank_mask:0xf
	v_pk_mul_f32 v[26:27], v[20:21], s[98:99] op_sel_hi:[1,0]
	v_exp_f32_e32 v26, v26
	v_exp_f32_e32 v27, v27
	v_mov_b32_dpp v34, v18 row_ror:1 row_mask:0xf bank_mask:0xf
	v_mov_b32_dpp v40, v19 row_ror:1 row_mask:0xf bank_mask:0xf
	v_cndmask_b32_e64 v29, v69, v41, s[6:7]
	v_cndmask_b32_e64 v28, v47, v35, s[6:7]
	v_pk_mul_f32 v[22:23], v[22:23], v[24:25]
	v_add_f32_e32 v24, 1.0, v26
	v_add_f32_e32 v25, 1.0, v27
	v_cndmask_b32_e64 v27, v40, v68, s[4:5]
	v_cndmask_b32_e64 v26, v34, v46, s[4:5]
	v_pk_mul_f32 v[28:29], v[88:89], v[28:29]
	v_rcp_f32_e32 v24, v24
	v_pk_fma_f32 v[26:27], v[92:93], v[26:27], v[28:29]
	v_rcp_f32_e32 v25, v25
	v_pk_fma_f32 v[18:19], v[18:19], v[96:97], v[26:27]
	v_pk_mul_f32 v[26:27], v[18:19], s[98:99] op_sel_hi:[1,0]
	v_exp_f32_e32 v26, v26
	v_exp_f32_e32 v27, v27
	v_mov_b32_dpp v43, v16 row_ror:2 row_mask:0xf bank_mask:0xf
	v_mov_b32_dpp v45, v17 row_ror:2 row_mask:0xf bank_mask:0xf
	v_mov_b32_dpp v42, v16 row_ror:1 row_mask:0xf bank_mask:0xf
	v_mov_b32_dpp v44, v17 row_ror:1 row_mask:0xf bank_mask:0xf
	v_cndmask_b32_e64 v29, v65, v45, s[6:7]
	v_cndmask_b32_e64 v28, v55, v43, s[6:7]
	v_pk_mul_f32 v[20:21], v[20:21], v[24:25]
	v_add_f32_e32 v24, 1.0, v26
	v_add_f32_e32 v25, 1.0, v27
	v_cndmask_b32_e64 v27, v44, v64, s[4:5]
	v_cndmask_b32_e64 v26, v42, v54, s[4:5]
	v_pk_mul_f32 v[28:29], v[90:91], v[28:29]
	v_rcp_f32_e32 v24, v24
	v_pk_fma_f32 v[26:27], v[94:95], v[26:27], v[28:29]
	v_rcp_f32_e32 v25, v25
	v_pk_fma_f32 v[16:17], v[16:17], v[98:99], v[26:27]
	v_pk_mul_f32 v[14:15], v[14:15], v[20:21]
	v_pk_mul_f32 v[26:27], v[16:17], s[98:99] op_sel_hi:[1,0]
	v_exp_f32_e32 v26, v26
	v_exp_f32_e32 v27, v27
	v_pk_mul_f32 v[18:19], v[18:19], v[24:25]
	v_pk_mul_f32 v[4:5], v[4:5], v[214:215]
	v_pk_add_f32 v[26:27], v[26:27], 1.0 op_sel_hi:[1,0]
	v_rcp_f32_e32 v26, v26
	v_rcp_f32_e32 v27, v27
	v_pk_mul_f32 v[18:19], v[8:9], v[18:19]
; __device__ __forceinline__ u32x4 pack8(f32x4 a, f32x4 b) { u32x4 w; w.x = cvtpk(a[0], a[1]); w.y = cvtpk(a[2], a[3]); w.z = cvtpk(b[0], b[1]); w.w = cvtpk(b[2], b[3]); return w; }
; #define PG8_BAR __builtin_amdgcn_s_barrier()
; __device__ __forceinline__ float dpp_ror1(float v) { return __builtin_bit_cast(float, __builtin_amdgcn_update_dpp(0, __builtin_bit_cast(int, v), 0x121, 0xf, 0xf, false)); }
; __device__ __forceinline__ float dpp_ror2(float v) { return __builtin_bit_cast(float, __builtin_amdgcn_update_dpp(0, __builtin_bit_cast(int, v), 0x122, 0xf, 0xf, false)); }
; __device__ __forceinline__ float silu_mul(float cv, float g) { return cv * __builtin_amdgcn_rcpf(1.f + __builtin_amdgcn_exp2f(-cv * LOG2E)) * g; }
; template <class Epi>
; __device__ __forceinline__ void gemm_phase(LAS unsigned char* lds, const bf16_t* A0, const bf16_t* B0, const bf16_t* A1, const bf16_t* B1, const int K, const Order& S, const Epi& E) {
;     ...
;         cur = nxt; cA = nA; cB = nB; ++ui;
;         if (wr == 1) PG8_BAR;
;     __device__ __forceinline__ void operator()(f32x4 (&acc)[2][2][4][2], const Unit& u, int wr, int wc, int fr, int fq) const {
;     ...
;             for (int m = 0; m < 4; ++m) {
;                 const int grow = u.pm * BM + ai * HALF + wr * 64 + m * 16 + fr;
;                 f32x4 av[2];
; #pragma unroll
;                 for (int n = 0; n < 2; ++n)
; #pragma unroll
;                     for (int e = 0; e < 4; ++e) {
;                         const float cur = acc[ai][0][m][n][e], prv = pv[n][e];
;                         const float a1 = dpp_ror1(cur), b1 = dpp_ror1(prv), a2 = dpp_ror2(cur), b2 = dpp_ror2(prv);
;                         const float p1 = fr >= 1 ? a1 : b1, p2 = fr >= 2 ? a2 : b2;
;                         const float cv = w0[n][e] * p2 + w1[n][e] * p1 + w2[n][e] * cur;
;                         av[n][e] = silu_mul(cv, acc[ai][1][m][n][e]);
;                     }
;                 *(u32x4*)(ACT + (size_t)grow * DFF + f0) = pack8(av[0], av[1]);
;                 pv[0] = acc[ai][0][m][0]; pv[1] = acc[ai][0][m][1];
;             }
	v_pk_mul_f32 v[0:1], v[0:1], v[214:215]
	s_andn2_b64 vcc, exec, s[68:69]
	v_pk_mul_f32 v[8:9], v[16:17], v[26:27]
	s_nop 0
	v_pk_mul_f32 v[16:17], v[10:11], v[8:9]
	v_cvt_pk_bf16_f32 v10, v18, v19
	v_cvt_pk_bf16_f32 v9, v14, v15
	v_mov_b32_dpp v18, v60 row_ror:2 row_mask:0xf bank_mask:0xf
	v_mov_b32_dpp v19, v61 row_ror:2 row_mask:0xf bank_mask:0xf
	v_mov_b32_dpp v11, v60 row_ror:1 row_mask:0xf bank_mask:0xf
	v_mov_b32_dpp v14, v61 row_ror:1 row_mask:0xf bank_mask:0xf
	v_cndmask_b32_e64 v19, v39, v19, s[6:7]
	v_cndmask_b32_e64 v18, v37, v18, s[6:7]
	v_cndmask_b32_e64 v15, v14, v38, s[4:5]
	v_cndmask_b32_e64 v14, v11, v36, s[4:5]
	v_pk_mul_f32 v[18:19], v[100:101], v[18:19]
	v_cvt_pk_bf16_f32 v8, v22, v23
	v_pk_fma_f32 v[14:15], v[104:105], v[14:15], v[18:19]
	s_nop 0
	v_pk_fma_f32 v[14:15], v[60:61], v[108:109], v[14:15]
	s_nop 0
	v_mul_f32_e32 v11, 0xbfb8aa3b, v14
	v_exp_f32_e32 v18, v11
	v_mul_f32_e32 v11, 0xbfb8aa3b, v15
	v_exp_f32_e32 v19, v11
	v_cvt_pk_bf16_f32 v11, v16, v17
	v_add_f32_e32 v16, 1.0, v18
	v_rcp_f32_e32 v16, v16
	v_add_f32_e32 v17, 1.0, v19
	v_rcp_f32_e32 v17, v17
	v_mad_i64_i32 v[18:19], s[0:1], v206, s94, v[12:13]
	v_lshl_add_u64 v[18:19], v[18:19], 0, v[112:113]
	global_store_dwordx4 v[18:19], v[8:11], off
	s_nop 1
	v_pk_mul_f32 v[8:9], v[14:15], v[16:17]
	v_mov_b32_dpp v14, v62 row_ror:2 row_mask:0xf bank_mask:0xf
	v_mov_b32_dpp v15, v63 row_ror:2 row_mask:0xf bank_mask:0xf
	v_mov_b32_dpp v10, v62 row_ror:1 row_mask:0xf bank_mask:0xf
	v_mov_b32_dpp v11, v63 row_ror:1 row_mask:0xf bank_mask:0xf
	v_cndmask_b32_e64 v15, v33, v15, s[6:7]
	v_cndmask_b32_e64 v14, v31, v14, s[6:7]
	v_cndmask_b32_e64 v11, v11, v32, s[4:5]
	v_cndmask_b32_e64 v10, v10, v30, s[4:5]
	v_pk_mul_f32 v[14:15], v[102:103], v[14:15]
	v_pk_fma_f32 v[10:11], v[106:107], v[10:11], v[14:15]
	v_pk_fma_f32 v[10:11], v[62:63], v[110:111], v[10:11]
	v_pk_mul_f32 v[4:5], v[4:5], v[8:9]
	v_pk_mul_f32 v[14:15], v[10:11], s[98:99] op_sel_hi:[1,0]
	v_exp_f32_e32 v14, v14
	v_exp_f32_e32 v15, v15
	v_mov_b32_dpp v16, v56 row_ror:2 row_mask:0xf bank_mask:0xf
	v_mov_b32_dpp v17, v57 row_ror:2 row_mask:0xf bank_mask:0xf
	v_add_f32_e32 v8, 1.0, v14
	v_add_f32_e32 v9, 1.0, v15
	v_cndmask_b32_e64 v17, v41, v17, s[6:7]
	v_mov_b32_dpp v14, v56 row_ror:1 row_mask:0xf bank_mask:0xf
	v_mov_b32_dpp v15, v57 row_ror:1 row_mask:0xf bank_mask:0xf
	v_cndmask_b32_e64 v16, v35, v16, s[6:7]
	v_cndmask_b32_e64 v15, v15, v40, s[4:5]
	v_cndmask_b32_e64 v14, v14, v34, s[4:5]
	v_pk_mul_f32 v[16:17], v[88:89], v[16:17]
	v_rcp_f32_e32 v8, v8
	v_pk_fma_f32 v[14:15], v[92:93], v[14:15], v[16:17]
	v_rcp_f32_e32 v9, v9
	v_pk_fma_f32 v[14:15], v[56:57], v[96:97], v[14:15]
	v_mov_b32_dpp v18, v58 row_ror:2 row_mask:0xf bank_mask:0xf
	v_pk_mul_f32 v[16:17], v[14:15], s[98:99] op_sel_hi:[1,0]
	v_exp_f32_e32 v16, v16
	v_exp_f32_e32 v17, v17
	v_pk_mul_f32 v[8:9], v[10:11], v[8:9]
	v_mov_b32_dpp v19, v59 row_ror:2 row_mask:0xf bank_mask:0xf
	v_add_f32_e32 v10, 1.0, v16
	v_add_f32_e32 v11, 1.0, v17
	v_cndmask_b32_e64 v19, v45, v19, s[6:7]
	v_mov_b32_dpp v16, v58 row_ror:1 row_mask:0xf bank_mask:0xf
	v_mov_b32_dpp v17, v59 row_ror:1 row_mask:0xf bank_mask:0xf
	v_cndmask_b32_e64 v18, v43, v18, s[6:7]
	v_cndmask_b32_e64 v17, v17, v44, s[4:5]
	v_cndmask_b32_e64 v16, v16, v42, s[4:5]
	v_pk_mul_f32 v[18:19], v[90:91], v[18:19]
	v_rcp_f32_e32 v10, v10
	v_pk_fma_f32 v[16:17], v[94:95], v[16:17], v[18:19]
	v_rcp_f32_e32 v11, v11
	v_pk_fma_f32 v[16:17], v[58:59], v[98:99], v[16:17]
	v_pk_mul_f32 v[6:7], v[6:7], v[8:9]
	v_pk_mul_f32 v[18:19], v[16:17], s[98:99] op_sel_hi:[1,0]
	v_exp_f32_e32 v18, v18
	v_exp_f32_e32 v19, v19
	v_pk_mul_f32 v[8:9], v[14:15], v[10:11]
	v_pk_add_f32 v[18:19], v[18:19], 1.0 op_sel_hi:[1,0]
	v_rcp_f32_e32 v18, v18
	v_rcp_f32_e32 v19, v19
	v_pk_mul_f32 v[8:9], v[0:1], v[8:9]
	v_pk_mul_f32 v[0:1], v[16:17], v[18:19]
	s_nop 0
	v_pk_mul_f32 v[10:11], v[2:3], v[0:1]
	v_cvt_pk_bf16_f32 v0, v4, v5
	v_mad_i64_i32 v[4:5], s[0:1], v202, s94, v[12:13]
	v_cvt_pk_bf16_f32 v1, v6, v7
	v_cvt_pk_bf16_f32 v2, v8, v9
	v_cvt_pk_bf16_f32 v3, v10, v11
	v_lshl_add_u64 v[4:5], v[4:5], 0, v[112:113]
	s_mov_b64 s[0:1], -1
	global_store_dwordx4 v[4:5], v[0:3], off
	s_cbranch_vccnz .LBB0_1149
	s_branch .LBB0_1148
